# back-edge rotation (7.11): K-loop counter update and exit test moved in front of the loop-back barrier
# baseline (speedup 1.0000x reference)
; #define PG8_STAGE(bufoff, gbase, voff) do { _Pragma("unroll") for (int _i = 0; _i < 2; ++_i) \
;         __builtin_amdgcn_global_load_lds((const unsigned*)((const char*)(gbase) + (voff)[_i]), (PG8_LAS unsigned*)(lds + (bufoff) + ldsw + _i * 8192), 16, 0, 0); } while (0)
; #define PG8_LDA(dst, b, h) do { _Pragma("unroll") for (int m = 0; m < 4; ++m) _Pragma("unroll") for (int k = 0; k < 2; ++k) dst[m][k] = *(const PG8_LAS bf16x8*)(lds + PG8_SA(b, h) + aoff + m * 2048 + k * 1024); } while (0)
; #define PG8_LDB(dst, b, h) do { _Pragma("unroll") for (int n = 0; n < 2; ++n) _Pragma("unroll") for (int k = 0; k < 2; ++k) dst[n][k] = *(const PG8_LAS bf16x8*)(lds + PG8_SB(b, h) + boff + n * 2048 + k * 1024); } while (0)
; #define PG8_MMA(ai, bj, At, Bt) do { __builtin_amdgcn_s_setprio(1); _Pragma("unroll") for (int m = 0; m < 4; ++m) _Pragma("unroll") for (int n = 0; n < 2; ++n) _Pragma("unroll") for (int k = 0; k < 2; ++k) \
;         acc[ai][bj][m][n] = __builtin_amdgcn_mfma_f32_16x16x32_bf16(Bt[n][k], At[m][k], acc[ai][bj][m][n], 0, 0, 0); __builtin_amdgcn_s_setprio(0); } while (0)
; #define PG8_WAIT_V(n) asm volatile("s_waitcnt vmcnt(" #n ")" ::: "memory")
; #define PG8_WAIT_L(n) asm volatile("s_waitcnt lgkmcnt(" #n ")" ::: "memory")
; #define PG8_BAR __builtin_amdgcn_s_barrier()
; #define PG8_SCHED __builtin_amdgcn_sched_barrier(0)
; template <class Epi, class Sched, bool ALIGN_EPI = false, bool SP2 = false>
; __device__ __forceinline__ void gemm_phase(PG8_LAS unsigned char* lds, const Gemm g, const Sched& S, const Epi& E, const int wave_) {
;     ...
;             const char* a1 = cA + (size_t)(t + 1) * kstep;
;             const char* a2 = last ? nA : cA + (size_t)(t + 2) * kstep; const char* b2 = last ? nB : cB + (size_t)(t + 2) * kstep;
;             const char* a3 = a2 + kstep; const char* b3 = b2 + kstep;
;     ...
;             PG8_LDB(B0, 0, 0); PG8_LDB(B1, 0, 1); PG8_SCHED; PG8_LDA(At, 0, 0); PG8_STAGE(PG8_SA(1, 1), a1 + hstep, voffA);
;             PG8_WAIT_V(8); PG8_WAIT_L(0); PG8_BAR; PG8_MMA(0, 0, At, B0); PG8_MMA(0, 1, At, B1); PG8_BAR; PG8_SCHED;
;             PG8_LDA(At, 0, 1); PG8_STAGE(PG8_SB(0, 0), b2, voffB); PG8_STAGE(PG8_SB(0, 1), b2 + hstep, voffB); PG8_STAGE(PG8_SA(0, 0), a2, voffA);
.LBB0_129:
	s_waitcnt lgkmcnt(0)
	ds_read_b128 v[158:161], v202
	ds_read_b128 v[162:165], v202 offset:1024
	ds_read_b128 v[166:169], v202 offset:2048
	ds_read_b128 v[170:173], v202 offset:3072
	ds_read_b128 v[174:177], v205
	ds_read_b128 v[178:181], v205 offset:1024
	ds_read_b128 v[182:185], v205 offset:2048
	ds_read_b128 v[186:189], v205 offset:3072
	s_add_u32 s23, s46, 0xfff80080
	s_addc_u32 s24, s47, -1
	s_cmp_eq_u32 s22, 28
	s_cselect_b32 s51, s19, s24
	s_cselect_b32 s50, s39, s23
	s_cselect_b32 s49, s37, s97
	s_cselect_b32 s48, vcc_lo, vcc_hi
	v_lshl_add_u64 v[238:239], s[46:47], 0, v[148:149]
	s_add_i32 m0, s53, 0xc000
	ds_read_b128 v[206:209], v203
	ds_read_b128 v[210:213], v203 offset:1024
	ds_read_b128 v[214:217], v203 offset:2048
	ds_read_b128 v[218:221], v203 offset:3072
	ds_read_b128 v[222:225], v203 offset:4096
	ds_read_b128 v[226:229], v203 offset:5120
	ds_read_b128 v[230:233], v203 offset:6144
	ds_read_b128 v[234:237], v203 offset:7168
	global_load_lds_dwordx4 v[238:239], off
	v_lshl_add_u64 v[238:239], s[46:47], 0, v[150:151]
	s_add_i32 m0, s53, 0xe000
	s_nop 0
	global_load_lds_dwordx4 v[238:239], off
	s_waitcnt vmcnt(8)
	s_waitcnt lgkmcnt(0)
	s_barrier
	s_setprio 1
	s_waitcnt lgkmcnt(0)
	v_mfma_f32_16x16x32_bf16 v[124:127], v[158:161], v[206:209], v[124:127]
	v_mfma_f32_16x16x32_bf16 v[116:119], v[166:169], v[206:209], v[116:119]
	v_mfma_f32_16x16x32_bf16 v[108:111], v[158:161], v[214:217], v[108:111]
	v_mfma_f32_16x16x32_bf16 v[100:103], v[166:169], v[214:217], v[100:103]
	v_mfma_f32_16x16x32_bf16 v[92:95], v[158:161], v[222:225], v[92:95]
	v_mfma_f32_16x16x32_bf16 v[84:87], v[166:169], v[222:225], v[84:87]
	v_mfma_f32_16x16x32_bf16 v[76:79], v[158:161], v[230:233], v[76:79]
	v_mfma_f32_16x16x32_bf16 v[68:71], v[166:169], v[230:233], v[68:71]
	v_mfma_f32_16x16x32_bf16 v[124:127], v[162:165], v[210:213], v[124:127]
	v_mfma_f32_16x16x32_bf16 v[116:119], v[170:173], v[210:213], v[116:119]
	v_mfma_f32_16x16x32_bf16 v[108:111], v[162:165], v[218:221], v[108:111]
	v_mfma_f32_16x16x32_bf16 v[100:103], v[170:173], v[218:221], v[100:103]
	v_mfma_f32_16x16x32_bf16 v[92:95], v[162:165], v[226:229], v[92:95]
	v_mfma_f32_16x16x32_bf16 v[84:87], v[170:173], v[226:229], v[84:87]
	v_mfma_f32_16x16x32_bf16 v[76:79], v[162:165], v[234:237], v[76:79]
	v_mfma_f32_16x16x32_bf16 v[68:71], v[170:173], v[234:237], v[68:71]
	s_setprio 0
	s_setprio 1
	v_mfma_f32_16x16x32_bf16 v[120:123], v[174:177], v[206:209], v[120:123]
	v_mfma_f32_16x16x32_bf16 v[112:115], v[182:185], v[206:209], v[112:115]
	v_mfma_f32_16x16x32_bf16 v[104:107], v[174:177], v[214:217], v[104:107]
	v_mfma_f32_16x16x32_bf16 v[96:99], v[182:185], v[214:217], v[96:99]
	v_mfma_f32_16x16x32_bf16 v[88:91], v[174:177], v[222:225], v[88:91]
	v_mfma_f32_16x16x32_bf16 v[80:83], v[182:185], v[222:225], v[80:83]
	v_mfma_f32_16x16x32_bf16 v[72:75], v[174:177], v[230:233], v[72:75]
	v_mfma_f32_16x16x32_bf16 v[64:67], v[182:185], v[230:233], v[64:67]
	v_mfma_f32_16x16x32_bf16 v[120:123], v[178:181], v[210:213], v[120:123]
	v_mfma_f32_16x16x32_bf16 v[112:115], v[186:189], v[210:213], v[112:115]
	v_mfma_f32_16x16x32_bf16 v[104:107], v[178:181], v[218:221], v[104:107]
	v_mfma_f32_16x16x32_bf16 v[96:99], v[186:189], v[218:221], v[96:99]
	v_mfma_f32_16x16x32_bf16 v[88:91], v[178:181], v[226:229], v[88:91]
	v_mfma_f32_16x16x32_bf16 v[80:83], v[186:189], v[226:229], v[80:83]
	v_mfma_f32_16x16x32_bf16 v[72:75], v[178:181], v[234:237], v[72:75]
	v_mfma_f32_16x16x32_bf16 v[64:67], v[186:189], v[234:237], v[64:67]
	s_setprio 0
	s_barrier
	s_add_i32 s23, s67, s52
	v_lshl_add_u64 v[238:239], s[48:49], 0, v[130:131]
	s_mov_b32 m0, s23
	ds_read_b128 v[206:209], v203 offset:16384
	ds_read_b128 v[210:213], v203 offset:17408
	ds_read_b128 v[214:217], v203 offset:18432
	ds_read_b128 v[218:221], v203 offset:19456
	ds_read_b128 v[222:225], v203 offset:20480
	ds_read_b128 v[226:229], v203 offset:21504
	ds_read_b128 v[230:233], v203 offset:22528
	ds_read_b128 v[234:237], v203 offset:23552
	global_load_lds_dwordx4 v[238:239], off
	s_add_i32 m0, s23, 0x2000
	s_add_u32 s24, s48, 0x80000
	v_lshl_add_u64 v[240:241], s[48:49], 0, v[134:135]
	s_addc_u32 s25, s49, 0
	s_add_i32 s23, s71, s52
	global_load_lds_dwordx4 v[240:241], off
	v_lshl_add_u64 v[242:243], s[24:25], 0, v[130:131]
	s_mov_b32 m0, s23
	v_lshl_add_u64 v[244:245], s[50:51], 0, v[132:133]
	global_load_lds_dwordx4 v[242:243], off
	v_lshl_add_u64 v[242:243], s[24:25], 0, v[134:135]
	s_add_i32 m0, s23, 0x2000
	s_nop 0
	global_load_lds_dwordx4 v[242:243], off
	v_lshl_add_u64 v[242:243], s[50:51], 0, v[128:129]
	s_mov_b32 m0, s53
	s_nop 0
	global_load_lds_dwordx4 v[242:243], off
	s_mov_b32 m0, s54
	s_nop 0
	global_load_lds_dwordx4 v[244:245], off
	s_waitcnt vmcnt(8)
	s_waitcnt lgkmcnt(0)
	s_barrier
; #define PG8_STAGE(bufoff, gbase, voff) do { _Pragma("unroll") for (int _i = 0; _i < 2; ++_i) \
;         __builtin_amdgcn_global_load_lds((const unsigned*)((const char*)(gbase) + (voff)[_i]), (PG8_LAS unsigned*)(lds + (bufoff) + ldsw + _i * 8192), 16, 0, 0); } while (0)
; #define PG8_LDA(dst, b, h) do { _Pragma("unroll") for (int m = 0; m < 4; ++m) _Pragma("unroll") for (int k = 0; k < 2; ++k) dst[m][k] = *(const PG8_LAS bf16x8*)(lds + PG8_SA(b, h) + aoff + m * 2048 + k * 1024); } while (0)
; #define PG8_LDB(dst, b, h) do { _Pragma("unroll") for (int n = 0; n < 2; ++n) _Pragma("unroll") for (int k = 0; k < 2; ++k) dst[n][k] = *(const PG8_LAS bf16x8*)(lds + PG8_SB(b, h) + boff + n * 2048 + k * 1024); } while (0)
; #define PG8_MMA(ai, bj, At, Bt) do { __builtin_amdgcn_s_setprio(1); _Pragma("unroll") for (int m = 0; m < 4; ++m) _Pragma("unroll") for (int n = 0; n < 2; ++n) _Pragma("unroll") for (int k = 0; k < 2; ++k) \
;         acc[ai][bj][m][n] = __builtin_amdgcn_mfma_f32_16x16x32_bf16(Bt[n][k], At[m][k], acc[ai][bj][m][n], 0, 0, 0); __builtin_amdgcn_s_setprio(0); } while (0)
; #define PG8_WAIT_V(n) asm volatile("s_waitcnt vmcnt(" #n ")" ::: "memory")
; #define PG8_WAIT_L(n) asm volatile("s_waitcnt lgkmcnt(" #n ")" ::: "memory")
; #define PG8_BAR __builtin_amdgcn_s_barrier()
; #define PG8_SCHED __builtin_amdgcn_sched_barrier(0)
; template <class Epi, class Sched, bool ALIGN_EPI = false, bool SP2 = false>
; __device__ __forceinline__ void gemm_phase(PG8_LAS unsigned char* lds, const Gemm g, const Sched& S, const Epi& E, const int wave_) {
;     ...
;             PG8_WAIT_V(8); PG8_WAIT_L(0); PG8_BAR; PG8_MMA(1, 0, At, B0); PG8_MMA(1, 1, At, B1); PG8_BAR; PG8_SCHED;
;             PG8_LDB(B0, 1, 0); PG8_LDB(B1, 1, 1); PG8_SCHED; PG8_LDA(At, 1, 0); PG8_STAGE(PG8_SA(0, 1), a2 + hstep, voffA);
;             PG8_WAIT_V(8); PG8_WAIT_L(0); PG8_BAR; PG8_MMA(0, 0, At, B0); PG8_MMA(0, 1, At, B1); PG8_BAR; PG8_SCHED;
	s_setprio 1
	s_waitcnt lgkmcnt(0)
	v_mfma_f32_16x16x32_bf16 v[60:63], v[158:161], v[206:209], v[60:63]
	v_mfma_f32_16x16x32_bf16 v[52:55], v[166:169], v[206:209], v[52:55]
	v_mfma_f32_16x16x32_bf16 v[44:47], v[158:161], v[214:217], v[44:47]
	v_mfma_f32_16x16x32_bf16 v[36:39], v[166:169], v[214:217], v[36:39]
	v_mfma_f32_16x16x32_bf16 v[28:31], v[158:161], v[222:225], v[28:31]
	v_mfma_f32_16x16x32_bf16 v[20:23], v[166:169], v[222:225], v[20:23]
	v_mfma_f32_16x16x32_bf16 v[12:15], v[158:161], v[230:233], v[12:15]
	v_mfma_f32_16x16x32_bf16 v[4:7], v[166:169], v[230:233], v[4:7]
	v_mfma_f32_16x16x32_bf16 v[60:63], v[162:165], v[210:213], v[60:63]
	v_mfma_f32_16x16x32_bf16 v[52:55], v[170:173], v[210:213], v[52:55]
	v_mfma_f32_16x16x32_bf16 v[44:47], v[162:165], v[218:221], v[44:47]
	v_mfma_f32_16x16x32_bf16 v[36:39], v[170:173], v[218:221], v[36:39]
	v_mfma_f32_16x16x32_bf16 v[28:31], v[162:165], v[226:229], v[28:31]
	v_mfma_f32_16x16x32_bf16 v[20:23], v[170:173], v[226:229], v[20:23]
	v_mfma_f32_16x16x32_bf16 v[12:15], v[162:165], v[234:237], v[12:15]
	v_mfma_f32_16x16x32_bf16 v[4:7], v[170:173], v[234:237], v[4:7]
	s_setprio 0
	s_setprio 1
	v_mfma_f32_16x16x32_bf16 v[56:59], v[174:177], v[206:209], v[56:59]
	v_mfma_f32_16x16x32_bf16 v[48:51], v[182:185], v[206:209], v[48:51]
	v_mfma_f32_16x16x32_bf16 v[40:43], v[174:177], v[214:217], v[40:43]
	v_mfma_f32_16x16x32_bf16 v[32:35], v[182:185], v[214:217], v[32:35]
	v_mfma_f32_16x16x32_bf16 v[24:27], v[174:177], v[222:225], v[24:27]
	v_mfma_f32_16x16x32_bf16 v[16:19], v[182:185], v[222:225], v[16:19]
	v_mfma_f32_16x16x32_bf16 v[8:11], v[174:177], v[230:233], v[8:11]
	v_mfma_f32_16x16x32_bf16 v[0:3], v[182:185], v[230:233], v[0:3]
	v_mfma_f32_16x16x32_bf16 v[56:59], v[178:181], v[210:213], v[56:59]
	v_mfma_f32_16x16x32_bf16 v[48:51], v[186:189], v[210:213], v[48:51]
	v_mfma_f32_16x16x32_bf16 v[40:43], v[178:181], v[218:221], v[40:43]
	v_mfma_f32_16x16x32_bf16 v[32:35], v[186:189], v[218:221], v[32:35]
	v_mfma_f32_16x16x32_bf16 v[24:27], v[178:181], v[226:229], v[24:27]
	v_mfma_f32_16x16x32_bf16 v[16:19], v[186:189], v[226:229], v[16:19]
	v_mfma_f32_16x16x32_bf16 v[8:11], v[178:181], v[234:237], v[8:11]
	v_mfma_f32_16x16x32_bf16 v[0:3], v[186:189], v[234:237], v[0:3]
	s_setprio 0
	s_barrier
	s_add_i32 s23, 0, 0x18000
	s_add_i32 s86, 0, 0x1c000
	v_add_u32_e32 v170, s23, v191
	v_add_u32_e32 v186, s86, v191
	ds_read_b128 v[158:161], v170
	ds_read_b128 v[162:165], v170 offset:1024
	ds_read_b128 v[166:169], v170 offset:2048
	ds_read_b128 v[170:173], v170 offset:3072
	ds_read_b128 v[174:177], v186
	ds_read_b128 v[178:181], v186 offset:1024
	ds_read_b128 v[182:185], v186 offset:2048
	ds_read_b128 v[186:189], v186 offset:3072
	s_add_u32 s24, s50, 0x80000
	s_addc_u32 s25, s51, 0
	s_mov_b32 m0, s55
	v_lshl_add_u64 v[246:247], s[24:25], 0, v[128:129]
	ds_read_b128 v[206:209], v203 offset:32768
	ds_read_b128 v[210:213], v203 offset:33792
	ds_read_b128 v[214:217], v203 offset:34816
	ds_read_b128 v[218:221], v203 offset:35840
	ds_read_b128 v[222:225], v203 offset:36864
	ds_read_b128 v[226:229], v203 offset:37888
	ds_read_b128 v[230:233], v203 offset:38912
	ds_read_b128 v[234:237], v203 offset:39936
	global_load_lds_dwordx4 v[246:247], off
	v_lshl_add_u64 v[246:247], s[24:25], 0, v[132:133]
	s_mov_b32 m0, s56
	s_nop 0
	global_load_lds_dwordx4 v[246:247], off
	s_waitcnt vmcnt(8)
	s_waitcnt lgkmcnt(0)
	s_barrier
	s_setprio 1
	s_waitcnt lgkmcnt(0)
	v_mfma_f32_16x16x32_bf16 v[124:127], v[158:161], v[206:209], v[124:127]
	v_mfma_f32_16x16x32_bf16 v[116:119], v[166:169], v[206:209], v[116:119]
	v_mfma_f32_16x16x32_bf16 v[108:111], v[158:161], v[214:217], v[108:111]
	v_mfma_f32_16x16x32_bf16 v[100:103], v[166:169], v[214:217], v[100:103]
	v_mfma_f32_16x16x32_bf16 v[92:95], v[158:161], v[222:225], v[92:95]
	v_mfma_f32_16x16x32_bf16 v[84:87], v[166:169], v[222:225], v[84:87]
	v_mfma_f32_16x16x32_bf16 v[76:79], v[158:161], v[230:233], v[76:79]
	v_mfma_f32_16x16x32_bf16 v[68:71], v[166:169], v[230:233], v[68:71]
	v_mfma_f32_16x16x32_bf16 v[124:127], v[162:165], v[210:213], v[124:127]
	v_mfma_f32_16x16x32_bf16 v[116:119], v[170:173], v[210:213], v[116:119]
	v_mfma_f32_16x16x32_bf16 v[108:111], v[162:165], v[218:221], v[108:111]
	v_mfma_f32_16x16x32_bf16 v[100:103], v[170:173], v[218:221], v[100:103]
	v_mfma_f32_16x16x32_bf16 v[92:95], v[162:165], v[226:229], v[92:95]
	v_mfma_f32_16x16x32_bf16 v[84:87], v[170:173], v[226:229], v[84:87]
	v_mfma_f32_16x16x32_bf16 v[76:79], v[162:165], v[234:237], v[76:79]
	v_mfma_f32_16x16x32_bf16 v[68:71], v[170:173], v[234:237], v[68:71]
	s_setprio 0
	s_setprio 1
	v_mfma_f32_16x16x32_bf16 v[120:123], v[174:177], v[206:209], v[120:123]
	v_mfma_f32_16x16x32_bf16 v[112:115], v[182:185], v[206:209], v[112:115]
	v_mfma_f32_16x16x32_bf16 v[104:107], v[174:177], v[214:217], v[104:107]
	v_mfma_f32_16x16x32_bf16 v[96:99], v[182:185], v[214:217], v[96:99]
	v_mfma_f32_16x16x32_bf16 v[88:91], v[174:177], v[222:225], v[88:91]
	v_mfma_f32_16x16x32_bf16 v[80:83], v[182:185], v[222:225], v[80:83]
	v_mfma_f32_16x16x32_bf16 v[72:75], v[174:177], v[230:233], v[72:75]
	v_mfma_f32_16x16x32_bf16 v[64:67], v[182:185], v[230:233], v[64:67]
	v_mfma_f32_16x16x32_bf16 v[120:123], v[178:181], v[210:213], v[120:123]
	v_mfma_f32_16x16x32_bf16 v[112:115], v[186:189], v[210:213], v[112:115]
	v_mfma_f32_16x16x32_bf16 v[104:107], v[178:181], v[218:221], v[104:107]
	v_mfma_f32_16x16x32_bf16 v[96:99], v[186:189], v[218:221], v[96:99]
	v_mfma_f32_16x16x32_bf16 v[88:91], v[178:181], v[226:229], v[88:91]
	v_mfma_f32_16x16x32_bf16 v[80:83], v[186:189], v[226:229], v[80:83]
	v_mfma_f32_16x16x32_bf16 v[72:75], v[178:181], v[234:237], v[72:75]
	v_mfma_f32_16x16x32_bf16 v[64:67], v[186:189], v[234:237], v[64:67]
	s_setprio 0
	s_barrier
; #define PG8_STAGE(bufoff, gbase, voff) do { _Pragma("unroll") for (int _i = 0; _i < 2; ++_i) \
;         __builtin_amdgcn_global_load_lds((const unsigned*)((const char*)(gbase) + (voff)[_i]), (PG8_LAS unsigned*)(lds + (bufoff) + ldsw + _i * 8192), 16, 0, 0); } while (0)
; #define PG8_LDA(dst, b, h) do { _Pragma("unroll") for (int m = 0; m < 4; ++m) _Pragma("unroll") for (int k = 0; k < 2; ++k) dst[m][k] = *(const PG8_LAS bf16x8*)(lds + PG8_SA(b, h) + aoff + m * 2048 + k * 1024); } while (0)
; #define PG8_MMA(ai, bj, At, Bt) do { __builtin_amdgcn_s_setprio(1); _Pragma("unroll") for (int m = 0; m < 4; ++m) _Pragma("unroll") for (int n = 0; n < 2; ++n) _Pragma("unroll") for (int k = 0; k < 2; ++k) \
;         acc[ai][bj][m][n] = __builtin_amdgcn_mfma_f32_16x16x32_bf16(Bt[n][k], At[m][k], acc[ai][bj][m][n], 0, 0, 0); __builtin_amdgcn_s_setprio(0); } while (0)
; #define PG8_WAIT_V(n) asm volatile("s_waitcnt vmcnt(" #n ")" ::: "memory")
; #define PG8_WAIT_L(n) asm volatile("s_waitcnt lgkmcnt(" #n ")" ::: "memory")
; #define PG8_BAR __builtin_amdgcn_s_barrier()
; #define PG8_SCHED __builtin_amdgcn_sched_barrier(0)
; template <class Epi, class Sched, bool ALIGN_EPI = false, bool SP2 = false>
; __device__ __forceinline__ void gemm_phase(PG8_LAS unsigned char* lds, const Gemm g, const Sched& S, const Epi& E, const int wave_) {
;     ...
;         for (int t = 0; t < nt; t += 2) {
;             const bool last = (t == nt - 2);
;     ...
;             PG8_LDA(At, 1, 1); PG8_STAGE(PG8_SB(1, 0), b3, voffB); PG8_STAGE(PG8_SB(1, 1), b3 + hstep, voffB); PG8_STAGE(PG8_SA(1, 0), a3, voffA);
;             PG8_WAIT_V(8); PG8_WAIT_L(0); PG8_BAR; PG8_MMA(1, 0, At, B0); PG8_MMA(1, 1, At, B1); PG8_BAR; PG8_SCHED;
	s_add_i32 s23, s23, s52
	v_lshl_add_u64 v[238:239], v[238:239], 0, s[34:35]
	s_mov_b32 m0, s23
	ds_read_b128 v[206:209], v203 offset:49152
	ds_read_b128 v[210:213], v203 offset:50176
	ds_read_b128 v[214:217], v203 offset:51200
	ds_read_b128 v[218:221], v203 offset:52224
	ds_read_b128 v[222:225], v203 offset:53248
	ds_read_b128 v[226:229], v203 offset:54272
	ds_read_b128 v[230:233], v203 offset:55296
	ds_read_b128 v[234:237], v203 offset:56320
	global_load_lds_dwordx4 v[238:239], off
	s_add_i32 m0, s23, 0x2000
	s_add_u32 s24, s48, 0x80080
	v_lshl_add_u64 v[238:239], v[240:241], 0, s[34:35]
	s_addc_u32 s25, s49, 0
	s_add_i32 s23, s86, s52
	global_load_lds_dwordx4 v[238:239], off
	v_lshl_add_u64 v[238:239], s[24:25], 0, v[130:131]
	s_mov_b32 m0, s23
	s_nop 0
	global_load_lds_dwordx4 v[238:239], off
	v_lshl_add_u64 v[238:239], s[24:25], 0, v[134:135]
	s_add_i32 m0, s23, 0x2000
	s_nop 0
	global_load_lds_dwordx4 v[238:239], off
	v_lshl_add_u64 v[238:239], v[242:243], 0, s[34:35]
	s_mov_b32 m0, s64
	s_nop 0
	global_load_lds_dwordx4 v[238:239], off
	v_lshl_add_u64 v[238:239], v[244:245], 0, s[34:35]
	s_mov_b32 m0, s65
	s_nop 0
	global_load_lds_dwordx4 v[238:239], off
	s_waitcnt vmcnt(8)
	s_waitcnt lgkmcnt(0)
	s_barrier
	s_setprio 1
	s_waitcnt lgkmcnt(0)
	v_mfma_f32_16x16x32_bf16 v[60:63], v[158:161], v[206:209], v[60:63]
	v_mfma_f32_16x16x32_bf16 v[52:55], v[166:169], v[206:209], v[52:55]
	v_mfma_f32_16x16x32_bf16 v[44:47], v[158:161], v[214:217], v[44:47]
	v_mfma_f32_16x16x32_bf16 v[36:39], v[166:169], v[214:217], v[36:39]
	v_mfma_f32_16x16x32_bf16 v[28:31], v[158:161], v[222:225], v[28:31]
	v_mfma_f32_16x16x32_bf16 v[20:23], v[166:169], v[222:225], v[20:23]
	v_mfma_f32_16x16x32_bf16 v[12:15], v[158:161], v[230:233], v[12:15]
	v_mfma_f32_16x16x32_bf16 v[4:7], v[166:169], v[230:233], v[4:7]
	v_mfma_f32_16x16x32_bf16 v[60:63], v[162:165], v[210:213], v[60:63]
	v_mfma_f32_16x16x32_bf16 v[52:55], v[170:173], v[210:213], v[52:55]
	v_mfma_f32_16x16x32_bf16 v[44:47], v[162:165], v[218:221], v[44:47]
	v_mfma_f32_16x16x32_bf16 v[36:39], v[170:173], v[218:221], v[36:39]
	v_mfma_f32_16x16x32_bf16 v[28:31], v[162:165], v[226:229], v[28:31]
	v_mfma_f32_16x16x32_bf16 v[20:23], v[170:173], v[226:229], v[20:23]
	v_mfma_f32_16x16x32_bf16 v[12:15], v[162:165], v[234:237], v[12:15]
	v_mfma_f32_16x16x32_bf16 v[4:7], v[170:173], v[234:237], v[4:7]
	s_setprio 0
	s_setprio 1
	v_mfma_f32_16x16x32_bf16 v[56:59], v[174:177], v[206:209], v[56:59]
	v_mfma_f32_16x16x32_bf16 v[48:51], v[182:185], v[206:209], v[48:51]
	v_mfma_f32_16x16x32_bf16 v[40:43], v[174:177], v[214:217], v[40:43]
	v_mfma_f32_16x16x32_bf16 v[32:35], v[182:185], v[214:217], v[32:35]
	v_mfma_f32_16x16x32_bf16 v[24:27], v[174:177], v[222:225], v[24:27]
	v_mfma_f32_16x16x32_bf16 v[16:19], v[182:185], v[222:225], v[16:19]
	v_mfma_f32_16x16x32_bf16 v[8:11], v[174:177], v[230:233], v[8:11]
	v_mfma_f32_16x16x32_bf16 v[0:3], v[182:185], v[230:233], v[0:3]
	v_mfma_f32_16x16x32_bf16 v[56:59], v[178:181], v[210:213], v[56:59]
	v_mfma_f32_16x16x32_bf16 v[48:51], v[186:189], v[210:213], v[48:51]
	v_mfma_f32_16x16x32_bf16 v[40:43], v[178:181], v[218:221], v[40:43]
	v_mfma_f32_16x16x32_bf16 v[32:35], v[186:189], v[218:221], v[32:35]
	v_mfma_f32_16x16x32_bf16 v[24:27], v[178:181], v[226:229], v[24:27]
	v_mfma_f32_16x16x32_bf16 v[16:19], v[186:189], v[226:229], v[16:19]
	v_mfma_f32_16x16x32_bf16 v[8:11], v[178:181], v[234:237], v[8:11]
	v_mfma_f32_16x16x32_bf16 v[0:3], v[186:189], v[234:237], v[0:3]
	s_setprio 0
	s_add_i32 s22, s22, 2
	s_add_u32 s46, s46, 0x100
	s_addc_u32 s47, s47, 0
	s_add_u32 vcc_hi, vcc_hi, 0x100
	s_addc_u32 s97, s97, 0
	s_cmp_gt_u32 s22, 29
	s_barrier
	s_cbranch_scc0 .LBB0_129
	s_and_b64 vcc, exec, s[74:75]
	s_cbranch_vccz .LBB0_132
	s_barrier

; #define PG8_STAGE(bufoff, gbase, voff) do { _Pragma("unroll") for (int _i = 0; _i < 2; ++_i) \
;         __builtin_amdgcn_global_load_lds((const unsigned*)((const char*)(gbase) + (voff)[_i]), (PG8_LAS unsigned*)(lds + (bufoff) + ldsw + _i * 8192), 16, 0, 0); } while (0)
; #define PG8_LDA(dst, b, h) do { _Pragma("unroll") for (int m = 0; m < 4; ++m) _Pragma("unroll") for (int k = 0; k < 2; ++k) dst[m][k] = *(const PG8_LAS bf16x8*)(lds + PG8_SA(b, h) + aoff + m * 2048 + k * 1024); } while (0)
; #define PG8_LDB(dst, b, h) do { _Pragma("unroll") for (int n = 0; n < 2; ++n) _Pragma("unroll") for (int k = 0; k < 2; ++k) dst[n][k] = *(const PG8_LAS bf16x8*)(lds + PG8_SB(b, h) + boff + n * 2048 + k * 1024); } while (0)
; #define PG8_MMA(ai, bj, At, Bt) do { __builtin_amdgcn_s_setprio(1); _Pragma("unroll") for (int m = 0; m < 4; ++m) _Pragma("unroll") for (int n = 0; n < 2; ++n) _Pragma("unroll") for (int k = 0; k < 2; ++k) \
;         acc[ai][bj][m][n] = __builtin_amdgcn_mfma_f32_16x16x32_bf16(Bt[n][k], At[m][k], acc[ai][bj][m][n], 0, 0, 0); __builtin_amdgcn_s_setprio(0); } while (0)
; #define PG8_WAIT_V(n) asm volatile("s_waitcnt vmcnt(" #n ")" ::: "memory")
; #define PG8_WAIT_L(n) asm volatile("s_waitcnt lgkmcnt(" #n ")" ::: "memory")
; #define PG8_BAR __builtin_amdgcn_s_barrier()
; #define PG8_SCHED __builtin_amdgcn_sched_barrier(0)
; template <class Epi, class Sched, bool ALIGN_EPI = false, bool SP2 = false>
; __device__ __forceinline__ void gemm_phase(PG8_LAS unsigned char* lds, const Gemm g, const Sched& S, const Epi& E, const int wave_) {
;     ...
;             const char* a1 = cA + (size_t)(t + 1) * kstep;
;             const char* a2 = last ? nA : cA + (size_t)(t + 2) * kstep; const char* b2 = last ? nB : cB + (size_t)(t + 2) * kstep;
;             const char* a3 = a2 + kstep; const char* b3 = b2 + kstep;
;     ...
;             PG8_LDB(B0, 0, 0); PG8_LDB(B1, 0, 1); PG8_SCHED; PG8_LDA(At, 0, 0); PG8_STAGE(PG8_SA(1, 1), a1 + hstep, voffA);
;             PG8_WAIT_V(8); PG8_WAIT_L(0); PG8_BAR; PG8_MMA(0, 0, At, B0); PG8_MMA(0, 1, At, B1); PG8_BAR; PG8_SCHED;
;             PG8_LDA(At, 0, 1); PG8_STAGE(PG8_SB(0, 0), b2, voffB); PG8_STAGE(PG8_SB(0, 1), b2 + hstep, voffB); PG8_STAGE(PG8_SA(0, 0), a2, voffA);
.LBB0_402:
	ds_read_b128 v[128:131], v189
	ds_read_b128 v[132:135], v189 offset:1024
	ds_read_b128 v[136:139], v189 offset:2048
	ds_read_b128 v[140:143], v189 offset:3072
	ds_read_b128 v[144:147], v201
	ds_read_b128 v[148:151], v201 offset:1024
	ds_read_b128 v[180:183], v201 offset:2048
	ds_read_b128 v[184:187], v201 offset:3072
	s_add_u32 s30, s28, 0xfff00080
	s_addc_u32 s31, s29, -1
	s_cmp_eq_u32 s53, 60
	s_cselect_b32 s35, s19, s31
	s_cselect_b32 s34, s25, s30
	s_cselect_b32 s31, s17, s52
	s_cselect_b32 s30, s50, s51
	v_lshl_add_u64 v[170:171], s[28:29], 0, v[162:163]
	s_add_i32 m0, s27, 0xc000
	ds_read_b128 v[190:193], v202
	ds_read_b128 v[196:199], v202 offset:1024
	ds_read_b128 v[204:207], v202 offset:2048
	ds_read_b128 v[208:211], v202 offset:3072
	ds_read_b128 v[212:215], v202 offset:4096
	ds_read_b128 v[216:219], v202 offset:5120
	ds_read_b128 v[220:223], v202 offset:6144
	ds_read_b128 v[224:227], v202 offset:7168
	global_load_lds_dwordx4 v[170:171], off
	v_lshl_add_u64 v[170:171], s[28:29], 0, v[164:165]
	s_add_i32 m0, s27, 0xe000
	s_nop 0
	global_load_lds_dwordx4 v[170:171], off
	s_waitcnt vmcnt(8)
	s_waitcnt lgkmcnt(0)
	s_barrier
	s_setprio 1
	s_waitcnt lgkmcnt(0)
	v_mfma_f32_16x16x32_bf16 v[124:127], v[128:131], v[190:193], v[124:127]
	v_mfma_f32_16x16x32_bf16 v[120:123], v[136:139], v[190:193], v[120:123]
	v_mfma_f32_16x16x32_bf16 v[108:111], v[128:131], v[204:207], v[108:111]
	v_mfma_f32_16x16x32_bf16 v[104:107], v[136:139], v[204:207], v[104:107]
	v_mfma_f32_16x16x32_bf16 v[92:95], v[128:131], v[212:215], v[92:95]
	v_mfma_f32_16x16x32_bf16 v[88:91], v[136:139], v[212:215], v[88:91]
	v_mfma_f32_16x16x32_bf16 v[76:79], v[128:131], v[220:223], v[76:79]
	v_mfma_f32_16x16x32_bf16 v[72:75], v[136:139], v[220:223], v[72:75]
	v_mfma_f32_16x16x32_bf16 v[124:127], v[132:135], v[196:199], v[124:127]
	v_mfma_f32_16x16x32_bf16 v[120:123], v[140:143], v[196:199], v[120:123]
	v_mfma_f32_16x16x32_bf16 v[108:111], v[132:135], v[208:211], v[108:111]
	v_mfma_f32_16x16x32_bf16 v[104:107], v[140:143], v[208:211], v[104:107]
	v_mfma_f32_16x16x32_bf16 v[92:95], v[132:135], v[216:219], v[92:95]
	v_mfma_f32_16x16x32_bf16 v[88:91], v[140:143], v[216:219], v[88:91]
	v_mfma_f32_16x16x32_bf16 v[76:79], v[132:135], v[224:227], v[76:79]
	v_mfma_f32_16x16x32_bf16 v[72:75], v[140:143], v[224:227], v[72:75]
	s_setprio 0
	s_setprio 1
	v_mfma_f32_16x16x32_bf16 v[116:119], v[144:147], v[190:193], v[116:119]
	v_mfma_f32_16x16x32_bf16 v[112:115], v[180:183], v[190:193], v[112:115]
	v_mfma_f32_16x16x32_bf16 v[100:103], v[144:147], v[204:207], v[100:103]
	v_mfma_f32_16x16x32_bf16 v[96:99], v[180:183], v[204:207], v[96:99]
	v_mfma_f32_16x16x32_bf16 v[84:87], v[144:147], v[212:215], v[84:87]
	v_mfma_f32_16x16x32_bf16 v[80:83], v[180:183], v[212:215], v[80:83]
	v_mfma_f32_16x16x32_bf16 v[68:71], v[144:147], v[220:223], v[68:71]
	v_mfma_f32_16x16x32_bf16 v[64:67], v[180:183], v[220:223], v[64:67]
	v_mfma_f32_16x16x32_bf16 v[116:119], v[148:151], v[196:199], v[116:119]
	v_mfma_f32_16x16x32_bf16 v[112:115], v[184:187], v[196:199], v[112:115]
	v_mfma_f32_16x16x32_bf16 v[100:103], v[148:151], v[208:211], v[100:103]
	v_mfma_f32_16x16x32_bf16 v[96:99], v[184:187], v[208:211], v[96:99]
	v_mfma_f32_16x16x32_bf16 v[84:87], v[148:151], v[216:219], v[84:87]
	v_mfma_f32_16x16x32_bf16 v[80:83], v[184:187], v[216:219], v[80:83]
	v_mfma_f32_16x16x32_bf16 v[68:71], v[148:151], v[224:227], v[68:71]
	v_mfma_f32_16x16x32_bf16 v[64:67], v[184:187], v[224:227], v[64:67]
	s_setprio 0
	s_barrier
	s_add_i32 s54, s48, s36
	v_lshl_add_u64 v[170:171], s[30:31], 0, v[156:157]
	s_mov_b32 m0, s54
	ds_read_b128 v[190:193], v202 offset:16384
	ds_read_b128 v[196:199], v202 offset:17408
	ds_read_b128 v[204:207], v202 offset:18432
	ds_read_b128 v[208:211], v202 offset:19456
	ds_read_b128 v[212:215], v202 offset:20480
	ds_read_b128 v[216:219], v202 offset:21504
	ds_read_b128 v[220:223], v202 offset:22528
	ds_read_b128 v[224:227], v202 offset:23552
	global_load_lds_dwordx4 v[170:171], off
	s_add_i32 m0, s54, 0x2000
	s_add_u32 s54, s30, 0x100000
	v_lshl_add_u64 v[228:229], s[30:31], 0, v[160:161]
	s_addc_u32 s55, s31, 0
	s_add_i32 s56, s49, s36
	global_load_lds_dwordx4 v[228:229], off
	v_lshl_add_u64 v[230:231], s[54:55], 0, v[156:157]
	s_mov_b32 m0, s56
	v_lshl_add_u64 v[232:233], s[34:35], 0, v[158:159]
	global_load_lds_dwordx4 v[230:231], off
	v_lshl_add_u64 v[230:231], s[54:55], 0, v[160:161]
	s_add_i32 m0, s56, 0x2000
	s_nop 0
	global_load_lds_dwordx4 v[230:231], off
	v_lshl_add_u64 v[230:231], s[34:35], 0, v[154:155]
	s_mov_b32 m0, s27
	s_nop 0
	global_load_lds_dwordx4 v[230:231], off
	s_mov_b32 m0, s37
	s_nop 0
	global_load_lds_dwordx4 v[232:233], off
	s_waitcnt vmcnt(8)
	s_waitcnt lgkmcnt(0)
	s_barrier
; #define PG8_STAGE(bufoff, gbase, voff) do { _Pragma("unroll") for (int _i = 0; _i < 2; ++_i) \
;         __builtin_amdgcn_global_load_lds((const unsigned*)((const char*)(gbase) + (voff)[_i]), (PG8_LAS unsigned*)(lds + (bufoff) + ldsw + _i * 8192), 16, 0, 0); } while (0)
; #define PG8_LDA(dst, b, h) do { _Pragma("unroll") for (int m = 0; m < 4; ++m) _Pragma("unroll") for (int k = 0; k < 2; ++k) dst[m][k] = *(const PG8_LAS bf16x8*)(lds + PG8_SA(b, h) + aoff + m * 2048 + k * 1024); } while (0)
; #define PG8_LDB(dst, b, h) do { _Pragma("unroll") for (int n = 0; n < 2; ++n) _Pragma("unroll") for (int k = 0; k < 2; ++k) dst[n][k] = *(const PG8_LAS bf16x8*)(lds + PG8_SB(b, h) + boff + n * 2048 + k * 1024); } while (0)
; #define PG8_MMA(ai, bj, At, Bt) do { __builtin_amdgcn_s_setprio(1); _Pragma("unroll") for (int m = 0; m < 4; ++m) _Pragma("unroll") for (int n = 0; n < 2; ++n) _Pragma("unroll") for (int k = 0; k < 2; ++k) \
;         acc[ai][bj][m][n] = __builtin_amdgcn_mfma_f32_16x16x32_bf16(Bt[n][k], At[m][k], acc[ai][bj][m][n], 0, 0, 0); __builtin_amdgcn_s_setprio(0); } while (0)
; #define PG8_WAIT_V(n) asm volatile("s_waitcnt vmcnt(" #n ")" ::: "memory")
; #define PG8_WAIT_L(n) asm volatile("s_waitcnt lgkmcnt(" #n ")" ::: "memory")
; #define PG8_BAR __builtin_amdgcn_s_barrier()
; #define PG8_SCHED __builtin_amdgcn_sched_barrier(0)
; template <class Epi, class Sched, bool ALIGN_EPI = false, bool SP2 = false>
; __device__ __forceinline__ void gemm_phase(PG8_LAS unsigned char* lds, const Gemm g, const Sched& S, const Epi& E, const int wave_) {
;     ...
;             PG8_WAIT_V(8); PG8_WAIT_L(0); PG8_BAR; PG8_MMA(1, 0, At, B0); PG8_MMA(1, 1, At, B1); PG8_BAR; PG8_SCHED;
;             PG8_LDB(B0, 1, 0); PG8_LDB(B1, 1, 1); PG8_SCHED; PG8_LDA(At, 1, 0); PG8_STAGE(PG8_SA(0, 1), a2 + hstep, voffA);
;             PG8_WAIT_V(8); PG8_WAIT_L(0); PG8_BAR; PG8_MMA(0, 0, At, B0); PG8_MMA(0, 1, At, B1); PG8_BAR; PG8_SCHED;
	s_setprio 1
	s_waitcnt lgkmcnt(0)
	v_mfma_f32_16x16x32_bf16 v[60:63], v[128:131], v[190:193], v[60:63]
	v_mfma_f32_16x16x32_bf16 v[56:59], v[136:139], v[190:193], v[56:59]
	v_mfma_f32_16x16x32_bf16 v[44:47], v[128:131], v[204:207], v[44:47]
	v_mfma_f32_16x16x32_bf16 v[40:43], v[136:139], v[204:207], v[40:43]
	v_mfma_f32_16x16x32_bf16 v[28:31], v[128:131], v[212:215], v[28:31]
	v_mfma_f32_16x16x32_bf16 v[24:27], v[136:139], v[212:215], v[24:27]
	v_mfma_f32_16x16x32_bf16 v[12:15], v[128:131], v[220:223], v[12:15]
	v_mfma_f32_16x16x32_bf16 v[8:11], v[136:139], v[220:223], v[8:11]
	v_mfma_f32_16x16x32_bf16 v[60:63], v[132:135], v[196:199], v[60:63]
	v_mfma_f32_16x16x32_bf16 v[56:59], v[140:143], v[196:199], v[56:59]
	v_mfma_f32_16x16x32_bf16 v[44:47], v[132:135], v[208:211], v[44:47]
	v_mfma_f32_16x16x32_bf16 v[40:43], v[140:143], v[208:211], v[40:43]
	v_mfma_f32_16x16x32_bf16 v[28:31], v[132:135], v[216:219], v[28:31]
	v_mfma_f32_16x16x32_bf16 v[24:27], v[140:143], v[216:219], v[24:27]
	v_mfma_f32_16x16x32_bf16 v[12:15], v[132:135], v[224:227], v[12:15]
	v_mfma_f32_16x16x32_bf16 v[8:11], v[140:143], v[224:227], v[8:11]
	s_setprio 0
	s_setprio 1
	v_mfma_f32_16x16x32_bf16 v[52:55], v[144:147], v[190:193], v[52:55]
	v_mfma_f32_16x16x32_bf16 v[48:51], v[180:183], v[190:193], v[48:51]
	v_mfma_f32_16x16x32_bf16 v[36:39], v[144:147], v[204:207], v[36:39]
	v_mfma_f32_16x16x32_bf16 v[32:35], v[180:183], v[204:207], v[32:35]
	v_mfma_f32_16x16x32_bf16 v[20:23], v[144:147], v[212:215], v[20:23]
	v_mfma_f32_16x16x32_bf16 v[16:19], v[180:183], v[212:215], v[16:19]
	v_mfma_f32_16x16x32_bf16 v[4:7], v[144:147], v[220:223], v[4:7]
	v_mfma_f32_16x16x32_bf16 v[0:3], v[180:183], v[220:223], v[0:3]
	v_mfma_f32_16x16x32_bf16 v[52:55], v[148:151], v[196:199], v[52:55]
	v_mfma_f32_16x16x32_bf16 v[48:51], v[184:187], v[196:199], v[48:51]
	v_mfma_f32_16x16x32_bf16 v[36:39], v[148:151], v[208:211], v[36:39]
	v_mfma_f32_16x16x32_bf16 v[32:35], v[184:187], v[208:211], v[32:35]
	v_mfma_f32_16x16x32_bf16 v[20:23], v[148:151], v[216:219], v[20:23]
	v_mfma_f32_16x16x32_bf16 v[16:19], v[184:187], v[216:219], v[16:19]
	v_mfma_f32_16x16x32_bf16 v[4:7], v[148:151], v[224:227], v[4:7]
	v_mfma_f32_16x16x32_bf16 v[0:3], v[184:187], v[224:227], v[0:3]
	s_setprio 0
	s_barrier
	s_add_i32 s54, 0, 0x18000
	s_add_i32 s55, 0, 0x1c000
	v_add_u32_e32 v140, s54, v173
	v_add_u32_e32 v172, s55, v173
	ds_read_b128 v[128:131], v140
	ds_read_b128 v[132:135], v140 offset:1024
	ds_read_b128 v[136:139], v140 offset:2048
	ds_read_b128 v[140:143], v140 offset:3072
	ds_read_b128 v[144:147], v172
	ds_read_b128 v[148:151], v172 offset:1024
	ds_read_b128 v[180:183], v172 offset:2048
	ds_read_b128 v[184:187], v172 offset:3072
	s_add_u32 s34, s34, 0x100000
	s_addc_u32 s35, s35, 0
	s_mov_b32 m0, s40
	v_lshl_add_u64 v[234:235], s[34:35], 0, v[154:155]
	ds_read_b128 v[190:193], v202 offset:32768
	ds_read_b128 v[196:199], v202 offset:33792
	ds_read_b128 v[204:207], v202 offset:34816
	ds_read_b128 v[208:211], v202 offset:35840
	ds_read_b128 v[212:215], v202 offset:36864
	ds_read_b128 v[216:219], v202 offset:37888
	ds_read_b128 v[220:223], v202 offset:38912
	ds_read_b128 v[224:227], v202 offset:39936
	global_load_lds_dwordx4 v[234:235], off
	v_lshl_add_u64 v[234:235], s[34:35], 0, v[158:159]
	s_mov_b32 m0, s41
	s_nop 0
	global_load_lds_dwordx4 v[234:235], off
	s_waitcnt vmcnt(8)
	s_waitcnt lgkmcnt(0)
	s_barrier
	s_setprio 1
	s_waitcnt lgkmcnt(0)
	v_mfma_f32_16x16x32_bf16 v[124:127], v[128:131], v[190:193], v[124:127]
	v_mfma_f32_16x16x32_bf16 v[120:123], v[136:139], v[190:193], v[120:123]
	v_mfma_f32_16x16x32_bf16 v[108:111], v[128:131], v[204:207], v[108:111]
	v_mfma_f32_16x16x32_bf16 v[104:107], v[136:139], v[204:207], v[104:107]
	v_mfma_f32_16x16x32_bf16 v[92:95], v[128:131], v[212:215], v[92:95]
	v_mfma_f32_16x16x32_bf16 v[88:91], v[136:139], v[212:215], v[88:91]
	v_mfma_f32_16x16x32_bf16 v[76:79], v[128:131], v[220:223], v[76:79]
	v_mfma_f32_16x16x32_bf16 v[72:75], v[136:139], v[220:223], v[72:75]
	v_mfma_f32_16x16x32_bf16 v[124:127], v[132:135], v[196:199], v[124:127]
	v_mfma_f32_16x16x32_bf16 v[120:123], v[140:143], v[196:199], v[120:123]
	v_mfma_f32_16x16x32_bf16 v[108:111], v[132:135], v[208:211], v[108:111]
	v_mfma_f32_16x16x32_bf16 v[104:107], v[140:143], v[208:211], v[104:107]
	v_mfma_f32_16x16x32_bf16 v[92:95], v[132:135], v[216:219], v[92:95]
	v_mfma_f32_16x16x32_bf16 v[88:91], v[140:143], v[216:219], v[88:91]
	v_mfma_f32_16x16x32_bf16 v[76:79], v[132:135], v[224:227], v[76:79]
	v_mfma_f32_16x16x32_bf16 v[72:75], v[140:143], v[224:227], v[72:75]
	s_setprio 0
	s_setprio 1
	v_mfma_f32_16x16x32_bf16 v[116:119], v[144:147], v[190:193], v[116:119]
	v_mfma_f32_16x16x32_bf16 v[112:115], v[180:183], v[190:193], v[112:115]
	v_mfma_f32_16x16x32_bf16 v[100:103], v[144:147], v[204:207], v[100:103]
	v_mfma_f32_16x16x32_bf16 v[96:99], v[180:183], v[204:207], v[96:99]
	v_mfma_f32_16x16x32_bf16 v[84:87], v[144:147], v[212:215], v[84:87]
	v_mfma_f32_16x16x32_bf16 v[80:83], v[180:183], v[212:215], v[80:83]
	v_mfma_f32_16x16x32_bf16 v[68:71], v[144:147], v[220:223], v[68:71]
	v_mfma_f32_16x16x32_bf16 v[64:67], v[180:183], v[220:223], v[64:67]
	v_mfma_f32_16x16x32_bf16 v[116:119], v[148:151], v[196:199], v[116:119]
	v_mfma_f32_16x16x32_bf16 v[112:115], v[184:187], v[196:199], v[112:115]
	v_mfma_f32_16x16x32_bf16 v[100:103], v[148:151], v[208:211], v[100:103]
	v_mfma_f32_16x16x32_bf16 v[96:99], v[184:187], v[208:211], v[96:99]
	v_mfma_f32_16x16x32_bf16 v[84:87], v[148:151], v[216:219], v[84:87]
	v_mfma_f32_16x16x32_bf16 v[80:83], v[184:187], v[216:219], v[80:83]
	v_mfma_f32_16x16x32_bf16 v[68:71], v[148:151], v[224:227], v[68:71]
	v_mfma_f32_16x16x32_bf16 v[64:67], v[184:187], v[224:227], v[64:67]
	s_setprio 0
	s_barrier
; #define PG8_STAGE(bufoff, gbase, voff) do { _Pragma("unroll") for (int _i = 0; _i < 2; ++_i) \
;         __builtin_amdgcn_global_load_lds((const unsigned*)((const char*)(gbase) + (voff)[_i]), (PG8_LAS unsigned*)(lds + (bufoff) + ldsw + _i * 8192), 16, 0, 0); } while (0)
; #define PG8_LDA(dst, b, h) do { _Pragma("unroll") for (int m = 0; m < 4; ++m) _Pragma("unroll") for (int k = 0; k < 2; ++k) dst[m][k] = *(const PG8_LAS bf16x8*)(lds + PG8_SA(b, h) + aoff + m * 2048 + k * 1024); } while (0)
; #define PG8_MMA(ai, bj, At, Bt) do { __builtin_amdgcn_s_setprio(1); _Pragma("unroll") for (int m = 0; m < 4; ++m) _Pragma("unroll") for (int n = 0; n < 2; ++n) _Pragma("unroll") for (int k = 0; k < 2; ++k) \
;         acc[ai][bj][m][n] = __builtin_amdgcn_mfma_f32_16x16x32_bf16(Bt[n][k], At[m][k], acc[ai][bj][m][n], 0, 0, 0); __builtin_amdgcn_s_setprio(0); } while (0)
; #define PG8_WAIT_V(n) asm volatile("s_waitcnt vmcnt(" #n ")" ::: "memory")
; #define PG8_WAIT_L(n) asm volatile("s_waitcnt lgkmcnt(" #n ")" ::: "memory")
; #define PG8_BAR __builtin_amdgcn_s_barrier()
; #define PG8_SCHED __builtin_amdgcn_sched_barrier(0)
; template <class Epi, class Sched, bool ALIGN_EPI = false, bool SP2 = false>
; __device__ __forceinline__ void gemm_phase(PG8_LAS unsigned char* lds, const Gemm g, const Sched& S, const Epi& E, const int wave_) {
;     ...
;         for (int t = 0; t < nt; t += 2) {
;             const bool last = (t == nt - 2);
;     ...
;             PG8_LDA(At, 1, 1); PG8_STAGE(PG8_SB(1, 0), b3, voffB); PG8_STAGE(PG8_SB(1, 1), b3 + hstep, voffB); PG8_STAGE(PG8_SA(1, 0), a3, voffA);
;             PG8_WAIT_V(8); PG8_WAIT_L(0); PG8_BAR; PG8_MMA(1, 0, At, B0); PG8_MMA(1, 1, At, B1); PG8_BAR; PG8_SCHED;
	s_add_i32 s34, s54, s36
	v_lshl_add_u64 v[170:171], v[170:171], 0, s[14:15]
	s_mov_b32 m0, s34
	ds_read_b128 v[190:193], v202 offset:49152
	ds_read_b128 v[196:199], v202 offset:50176
	ds_read_b128 v[204:207], v202 offset:51200
	ds_read_b128 v[208:211], v202 offset:52224
	ds_read_b128 v[212:215], v202 offset:53248
	ds_read_b128 v[216:219], v202 offset:54272
	ds_read_b128 v[220:223], v202 offset:55296
	ds_read_b128 v[224:227], v202 offset:56320
	global_load_lds_dwordx4 v[170:171], off
	s_add_i32 m0, s34, 0x2000
	s_add_u32 s30, s30, 0x100080
	v_lshl_add_u64 v[170:171], v[228:229], 0, s[14:15]
	s_addc_u32 s31, s31, 0
	s_add_i32 s34, s55, s36
	global_load_lds_dwordx4 v[170:171], off
	v_lshl_add_u64 v[170:171], s[30:31], 0, v[156:157]
	s_mov_b32 m0, s34
	s_nop 0
	global_load_lds_dwordx4 v[170:171], off
	v_lshl_add_u64 v[170:171], s[30:31], 0, v[160:161]
	s_add_i32 m0, s34, 0x2000
	s_nop 0
	global_load_lds_dwordx4 v[170:171], off
	v_lshl_add_u64 v[170:171], v[230:231], 0, s[14:15]
	s_mov_b32 m0, s45
	s_nop 0
	global_load_lds_dwordx4 v[170:171], off
	v_lshl_add_u64 v[170:171], v[232:233], 0, s[14:15]
	s_mov_b32 m0, s46
	s_nop 0
	global_load_lds_dwordx4 v[170:171], off
	s_waitcnt vmcnt(8)
	s_waitcnt lgkmcnt(0)
	s_barrier
	s_setprio 1
	s_waitcnt lgkmcnt(0)
	v_mfma_f32_16x16x32_bf16 v[60:63], v[128:131], v[190:193], v[60:63]
	v_mfma_f32_16x16x32_bf16 v[56:59], v[136:139], v[190:193], v[56:59]
	v_mfma_f32_16x16x32_bf16 v[44:47], v[128:131], v[204:207], v[44:47]
	v_mfma_f32_16x16x32_bf16 v[40:43], v[136:139], v[204:207], v[40:43]
	v_mfma_f32_16x16x32_bf16 v[28:31], v[128:131], v[212:215], v[28:31]
	v_mfma_f32_16x16x32_bf16 v[24:27], v[136:139], v[212:215], v[24:27]
	v_mfma_f32_16x16x32_bf16 v[12:15], v[128:131], v[220:223], v[12:15]
	v_mfma_f32_16x16x32_bf16 v[8:11], v[136:139], v[220:223], v[8:11]
	v_mfma_f32_16x16x32_bf16 v[60:63], v[132:135], v[196:199], v[60:63]
	v_mfma_f32_16x16x32_bf16 v[56:59], v[140:143], v[196:199], v[56:59]
	v_mfma_f32_16x16x32_bf16 v[44:47], v[132:135], v[208:211], v[44:47]
	v_mfma_f32_16x16x32_bf16 v[40:43], v[140:143], v[208:211], v[40:43]
	v_mfma_f32_16x16x32_bf16 v[28:31], v[132:135], v[216:219], v[28:31]
	v_mfma_f32_16x16x32_bf16 v[24:27], v[140:143], v[216:219], v[24:27]
	v_mfma_f32_16x16x32_bf16 v[12:15], v[132:135], v[224:227], v[12:15]
	v_mfma_f32_16x16x32_bf16 v[8:11], v[140:143], v[224:227], v[8:11]
	s_setprio 0
	s_setprio 1
	v_mfma_f32_16x16x32_bf16 v[52:55], v[144:147], v[190:193], v[52:55]
	v_mfma_f32_16x16x32_bf16 v[48:51], v[180:183], v[190:193], v[48:51]
	v_mfma_f32_16x16x32_bf16 v[36:39], v[144:147], v[204:207], v[36:39]
	v_mfma_f32_16x16x32_bf16 v[32:35], v[180:183], v[204:207], v[32:35]
	v_mfma_f32_16x16x32_bf16 v[20:23], v[144:147], v[212:215], v[20:23]
	v_mfma_f32_16x16x32_bf16 v[16:19], v[180:183], v[212:215], v[16:19]
	v_mfma_f32_16x16x32_bf16 v[4:7], v[144:147], v[220:223], v[4:7]
	v_mfma_f32_16x16x32_bf16 v[0:3], v[180:183], v[220:223], v[0:3]
	v_mfma_f32_16x16x32_bf16 v[52:55], v[148:151], v[196:199], v[52:55]
	v_mfma_f32_16x16x32_bf16 v[48:51], v[184:187], v[196:199], v[48:51]
	v_mfma_f32_16x16x32_bf16 v[36:39], v[148:151], v[208:211], v[36:39]
	v_mfma_f32_16x16x32_bf16 v[32:35], v[184:187], v[208:211], v[32:35]
	v_mfma_f32_16x16x32_bf16 v[20:23], v[148:151], v[216:219], v[20:23]
	v_mfma_f32_16x16x32_bf16 v[16:19], v[184:187], v[216:219], v[16:19]
	v_mfma_f32_16x16x32_bf16 v[4:7], v[148:151], v[224:227], v[4:7]
	v_mfma_f32_16x16x32_bf16 v[0:3], v[184:187], v[224:227], v[0:3]
	s_setprio 0
	s_add_i32 s53, s53, 2
	s_add_u32 s28, s28, 0x100
	s_addc_u32 s29, s29, 0
	s_add_u32 s51, s51, 0x100
	s_addc_u32 s52, s52, 0
	s_cmp_gt_u32 s53, 61
	s_barrier
	s_cbranch_scc0 .LBB0_402
	s_and_b64 vcc, exec, s[12:13]
	s_cbranch_vccz .LBB0_405
	s_barrier

; #define PG8_STAGE(bufoff, gbase, voff) do { _Pragma("unroll") for (int _i = 0; _i < 2; ++_i) \
;         __builtin_amdgcn_global_load_lds((const unsigned*)((const char*)(gbase) + (voff)[_i]), (PG8_LAS unsigned*)(lds + (bufoff) + ldsw + _i * 8192), 16, 0, 0); } while (0)
; #define PG8_LDA(dst, b, h) do { _Pragma("unroll") for (int m = 0; m < 4; ++m) _Pragma("unroll") for (int k = 0; k < 2; ++k) dst[m][k] = *(const PG8_LAS bf16x8*)(lds + PG8_SA(b, h) + aoff + m * 2048 + k * 1024); } while (0)
; #define PG8_LDB(dst, b, h) do { _Pragma("unroll") for (int n = 0; n < 2; ++n) _Pragma("unroll") for (int k = 0; k < 2; ++k) dst[n][k] = *(const PG8_LAS bf16x8*)(lds + PG8_SB(b, h) + boff + n * 2048 + k * 1024); } while (0)
; #define PG8_MMA(ai, bj, At, Bt) do { __builtin_amdgcn_s_setprio(1); _Pragma("unroll") for (int m = 0; m < 4; ++m) _Pragma("unroll") for (int n = 0; n < 2; ++n) _Pragma("unroll") for (int k = 0; k < 2; ++k) \
;         acc[ai][bj][m][n] = __builtin_amdgcn_mfma_f32_16x16x32_bf16(Bt[n][k], At[m][k], acc[ai][bj][m][n], 0, 0, 0); __builtin_amdgcn_s_setprio(0); } while (0)
; #define PG8_WAIT_V(n) asm volatile("s_waitcnt vmcnt(" #n ")" ::: "memory")
; #define PG8_WAIT_L(n) asm volatile("s_waitcnt lgkmcnt(" #n ")" ::: "memory")
; #define PG8_BAR __builtin_amdgcn_s_barrier()
; #define PG8_SCHED __builtin_amdgcn_sched_barrier(0)
; template <class Epi, class Sched, bool ALIGN_EPI = false, bool SP2 = false>
; __device__ __forceinline__ void gemm_phase(PG8_LAS unsigned char* lds, const Gemm g, const Sched& S, const Epi& E, const int wave_) {
;     ...
;             const char* a1 = cA + (size_t)(t + 1) * kstep;
;             const char* a2 = last ? nA : cA + (size_t)(t + 2) * kstep; const char* b2 = last ? nB : cB + (size_t)(t + 2) * kstep;
;             const char* a3 = a2 + kstep; const char* b3 = b2 + kstep;
;     ...
;             PG8_LDB(B0, 0, 0); PG8_LDB(B1, 0, 1); PG8_SCHED; PG8_LDA(At, 0, 0); PG8_STAGE(PG8_SA(1, 1), a1 + hstep, voffA);
;             PG8_WAIT_V(8); PG8_WAIT_L(0); PG8_BAR; PG8_MMA(0, 0, At, B0); PG8_MMA(0, 1, At, B1); PG8_BAR; PG8_SCHED;
;             PG8_LDA(At, 0, 1); PG8_STAGE(PG8_SB(0, 0), b2, voffB); PG8_STAGE(PG8_SB(0, 1), b2 + hstep, voffB); PG8_STAGE(PG8_SA(0, 0), a2, voffA);
.LBB0_495:
	ds_read_b128 v[146:149], v164
	ds_read_b128 v[154:157], v164 offset:1024
	ds_read_b128 v[158:161], v164 offset:2048
	ds_read_b128 v[168:171], v164 offset:3072
	ds_read_b128 v[172:175], v165
	ds_read_b128 v[176:179], v165 offset:1024
	ds_read_b128 v[180:183], v165 offset:2048
	ds_read_b128 v[184:187], v165 offset:3072
	s_add_u32 s40, s36, 0xfff80080
	s_addc_u32 s41, s37, -1
	s_cmp_eq_u32 s63, 28
	s_cselect_b32 s43, s5, s41
	s_cselect_b32 s42, s7, s40
	s_cselect_b32 s41, s27, s62
	s_cselect_b32 s40, s29, s61
	v_lshl_add_u64 v[150:151], s[36:37], 0, v[138:139]
	s_add_i32 m0, s45, 0xc000
	ds_read_b128 v[188:191], v166
	ds_read_b128 v[196:199], v166 offset:1024
	ds_read_b128 v[200:203], v166 offset:2048
	ds_read_b128 v[204:207], v166 offset:3072
	ds_read_b128 v[208:211], v166 offset:4096
	ds_read_b128 v[212:215], v166 offset:5120
	ds_read_b128 v[216:219], v166 offset:6144
	ds_read_b128 v[220:223], v166 offset:7168
	global_load_lds_dwordx4 v[150:151], off
	v_lshl_add_u64 v[150:151], s[36:37], 0, v[140:141]
	s_add_i32 m0, s45, 0xe000
	s_nop 0
	global_load_lds_dwordx4 v[150:151], off
	s_waitcnt vmcnt(8)
	s_waitcnt lgkmcnt(0)
	s_barrier
	s_setprio 1
	s_waitcnt lgkmcnt(0)
	v_mfma_f32_16x16x32_bf16 v[124:127], v[146:149], v[188:191], v[124:127]
	v_mfma_f32_16x16x32_bf16 v[120:123], v[158:161], v[188:191], v[120:123]
	v_mfma_f32_16x16x32_bf16 v[108:111], v[146:149], v[200:203], v[108:111]
	v_mfma_f32_16x16x32_bf16 v[104:107], v[158:161], v[200:203], v[104:107]
	v_mfma_f32_16x16x32_bf16 v[92:95], v[146:149], v[208:211], v[92:95]
	v_mfma_f32_16x16x32_bf16 v[88:91], v[158:161], v[208:211], v[88:91]
	v_mfma_f32_16x16x32_bf16 v[76:79], v[146:149], v[216:219], v[76:79]
	v_mfma_f32_16x16x32_bf16 v[72:75], v[158:161], v[216:219], v[72:75]
	v_mfma_f32_16x16x32_bf16 v[124:127], v[154:157], v[196:199], v[124:127]
	v_mfma_f32_16x16x32_bf16 v[120:123], v[168:171], v[196:199], v[120:123]
	v_mfma_f32_16x16x32_bf16 v[108:111], v[154:157], v[204:207], v[108:111]
	v_mfma_f32_16x16x32_bf16 v[104:107], v[168:171], v[204:207], v[104:107]
	v_mfma_f32_16x16x32_bf16 v[92:95], v[154:157], v[212:215], v[92:95]
	v_mfma_f32_16x16x32_bf16 v[88:91], v[168:171], v[212:215], v[88:91]
	v_mfma_f32_16x16x32_bf16 v[76:79], v[154:157], v[220:223], v[76:79]
	v_mfma_f32_16x16x32_bf16 v[72:75], v[168:171], v[220:223], v[72:75]
	s_setprio 0
	s_setprio 1
	v_mfma_f32_16x16x32_bf16 v[116:119], v[172:175], v[188:191], v[116:119]
	v_mfma_f32_16x16x32_bf16 v[112:115], v[180:183], v[188:191], v[112:115]
	v_mfma_f32_16x16x32_bf16 v[100:103], v[172:175], v[200:203], v[100:103]
	v_mfma_f32_16x16x32_bf16 v[96:99], v[180:183], v[200:203], v[96:99]
	v_mfma_f32_16x16x32_bf16 v[84:87], v[172:175], v[208:211], v[84:87]
	v_mfma_f32_16x16x32_bf16 v[80:83], v[180:183], v[208:211], v[80:83]
	v_mfma_f32_16x16x32_bf16 v[68:71], v[172:175], v[216:219], v[68:71]
	v_mfma_f32_16x16x32_bf16 v[64:67], v[180:183], v[216:219], v[64:67]
	v_mfma_f32_16x16x32_bf16 v[116:119], v[176:179], v[196:199], v[116:119]
	v_mfma_f32_16x16x32_bf16 v[112:115], v[184:187], v[196:199], v[112:115]
	v_mfma_f32_16x16x32_bf16 v[100:103], v[176:179], v[204:207], v[100:103]
	v_mfma_f32_16x16x32_bf16 v[96:99], v[184:187], v[204:207], v[96:99]
	v_mfma_f32_16x16x32_bf16 v[84:87], v[176:179], v[212:215], v[84:87]
	v_mfma_f32_16x16x32_bf16 v[80:83], v[184:187], v[212:215], v[80:83]
	v_mfma_f32_16x16x32_bf16 v[68:71], v[176:179], v[220:223], v[68:71]
	v_mfma_f32_16x16x32_bf16 v[64:67], v[184:187], v[220:223], v[64:67]
	s_setprio 0
	s_barrier
	s_add_i32 s64, s55, s44
	v_lshl_add_u64 v[150:151], s[40:41], 0, v[130:131]
	s_mov_b32 m0, s64
	ds_read_b128 v[188:191], v166 offset:16384
	ds_read_b128 v[196:199], v166 offset:17408
	ds_read_b128 v[200:203], v166 offset:18432
	ds_read_b128 v[204:207], v166 offset:19456
	ds_read_b128 v[208:211], v166 offset:20480
	ds_read_b128 v[212:215], v166 offset:21504
	ds_read_b128 v[216:219], v166 offset:22528
	ds_read_b128 v[220:223], v166 offset:23552
	global_load_lds_dwordx4 v[150:151], off
	s_add_i32 m0, s64, 0x2000
	s_add_u32 s64, s40, 0x80000
	v_lshl_add_u64 v[192:193], s[40:41], 0, v[134:135]
	s_addc_u32 s65, s41, 0
	s_add_i32 s66, s56, s44
	global_load_lds_dwordx4 v[192:193], off
	v_lshl_add_u64 v[224:225], s[64:65], 0, v[130:131]
	s_mov_b32 m0, s66
	v_lshl_add_u64 v[226:227], s[42:43], 0, v[132:133]
	global_load_lds_dwordx4 v[224:225], off
	v_lshl_add_u64 v[224:225], s[64:65], 0, v[134:135]
	s_add_i32 m0, s66, 0x2000
	s_nop 0
	global_load_lds_dwordx4 v[224:225], off
	v_lshl_add_u64 v[224:225], s[42:43], 0, v[128:129]
	s_mov_b32 m0, s45
	s_nop 0
	global_load_lds_dwordx4 v[224:225], off
	s_mov_b32 m0, s46
	s_nop 0
	global_load_lds_dwordx4 v[226:227], off
	s_waitcnt vmcnt(8)
	s_waitcnt lgkmcnt(0)
	s_barrier
; #define PG8_STAGE(bufoff, gbase, voff) do { _Pragma("unroll") for (int _i = 0; _i < 2; ++_i) \
;         __builtin_amdgcn_global_load_lds((const unsigned*)((const char*)(gbase) + (voff)[_i]), (PG8_LAS unsigned*)(lds + (bufoff) + ldsw + _i * 8192), 16, 0, 0); } while (0)
; #define PG8_LDA(dst, b, h) do { _Pragma("unroll") for (int m = 0; m < 4; ++m) _Pragma("unroll") for (int k = 0; k < 2; ++k) dst[m][k] = *(const PG8_LAS bf16x8*)(lds + PG8_SA(b, h) + aoff + m * 2048 + k * 1024); } while (0)
; #define PG8_LDB(dst, b, h) do { _Pragma("unroll") for (int n = 0; n < 2; ++n) _Pragma("unroll") for (int k = 0; k < 2; ++k) dst[n][k] = *(const PG8_LAS bf16x8*)(lds + PG8_SB(b, h) + boff + n * 2048 + k * 1024); } while (0)
; #define PG8_MMA(ai, bj, At, Bt) do { __builtin_amdgcn_s_setprio(1); _Pragma("unroll") for (int m = 0; m < 4; ++m) _Pragma("unroll") for (int n = 0; n < 2; ++n) _Pragma("unroll") for (int k = 0; k < 2; ++k) \
;         acc[ai][bj][m][n] = __builtin_amdgcn_mfma_f32_16x16x32_bf16(Bt[n][k], At[m][k], acc[ai][bj][m][n], 0, 0, 0); __builtin_amdgcn_s_setprio(0); } while (0)
; #define PG8_WAIT_V(n) asm volatile("s_waitcnt vmcnt(" #n ")" ::: "memory")
; #define PG8_WAIT_L(n) asm volatile("s_waitcnt lgkmcnt(" #n ")" ::: "memory")
; #define PG8_BAR __builtin_amdgcn_s_barrier()
; #define PG8_SCHED __builtin_amdgcn_sched_barrier(0)
; template <class Epi, class Sched, bool ALIGN_EPI = false, bool SP2 = false>
; __device__ __forceinline__ void gemm_phase(PG8_LAS unsigned char* lds, const Gemm g, const Sched& S, const Epi& E, const int wave_) {
;     ...
;             PG8_WAIT_V(8); PG8_WAIT_L(0); PG8_BAR; PG8_MMA(1, 0, At, B0); PG8_MMA(1, 1, At, B1); PG8_BAR; PG8_SCHED;
;             PG8_LDB(B0, 1, 0); PG8_LDB(B1, 1, 1); PG8_SCHED; PG8_LDA(At, 1, 0); PG8_STAGE(PG8_SA(0, 1), a2 + hstep, voffA);
;             PG8_WAIT_V(8); PG8_WAIT_L(0); PG8_BAR; PG8_MMA(0, 0, At, B0); PG8_MMA(0, 1, At, B1); PG8_BAR; PG8_SCHED;
	s_setprio 1
	s_waitcnt lgkmcnt(0)
	v_mfma_f32_16x16x32_bf16 v[60:63], v[146:149], v[188:191], v[60:63]
	v_mfma_f32_16x16x32_bf16 v[56:59], v[158:161], v[188:191], v[56:59]
	v_mfma_f32_16x16x32_bf16 v[44:47], v[146:149], v[200:203], v[44:47]
	v_mfma_f32_16x16x32_bf16 v[40:43], v[158:161], v[200:203], v[40:43]
	v_mfma_f32_16x16x32_bf16 v[28:31], v[146:149], v[208:211], v[28:31]
	v_mfma_f32_16x16x32_bf16 v[24:27], v[158:161], v[208:211], v[24:27]
	v_mfma_f32_16x16x32_bf16 v[12:15], v[146:149], v[216:219], v[12:15]
	v_mfma_f32_16x16x32_bf16 v[8:11], v[158:161], v[216:219], v[8:11]
	v_mfma_f32_16x16x32_bf16 v[60:63], v[154:157], v[196:199], v[60:63]
	v_mfma_f32_16x16x32_bf16 v[56:59], v[168:171], v[196:199], v[56:59]
	v_mfma_f32_16x16x32_bf16 v[44:47], v[154:157], v[204:207], v[44:47]
	v_mfma_f32_16x16x32_bf16 v[40:43], v[168:171], v[204:207], v[40:43]
	v_mfma_f32_16x16x32_bf16 v[28:31], v[154:157], v[212:215], v[28:31]
	v_mfma_f32_16x16x32_bf16 v[24:27], v[168:171], v[212:215], v[24:27]
	v_mfma_f32_16x16x32_bf16 v[12:15], v[154:157], v[220:223], v[12:15]
	v_mfma_f32_16x16x32_bf16 v[8:11], v[168:171], v[220:223], v[8:11]
	s_setprio 0
	s_setprio 1
	v_mfma_f32_16x16x32_bf16 v[52:55], v[172:175], v[188:191], v[52:55]
	v_mfma_f32_16x16x32_bf16 v[48:51], v[180:183], v[188:191], v[48:51]
	v_mfma_f32_16x16x32_bf16 v[36:39], v[172:175], v[200:203], v[36:39]
	v_mfma_f32_16x16x32_bf16 v[32:35], v[180:183], v[200:203], v[32:35]
	v_mfma_f32_16x16x32_bf16 v[20:23], v[172:175], v[208:211], v[20:23]
	v_mfma_f32_16x16x32_bf16 v[16:19], v[180:183], v[208:211], v[16:19]
	v_mfma_f32_16x16x32_bf16 v[4:7], v[172:175], v[216:219], v[4:7]
	v_mfma_f32_16x16x32_bf16 v[0:3], v[180:183], v[216:219], v[0:3]
	v_mfma_f32_16x16x32_bf16 v[52:55], v[176:179], v[196:199], v[52:55]
	v_mfma_f32_16x16x32_bf16 v[48:51], v[184:187], v[196:199], v[48:51]
	v_mfma_f32_16x16x32_bf16 v[36:39], v[176:179], v[204:207], v[36:39]
	v_mfma_f32_16x16x32_bf16 v[32:35], v[184:187], v[204:207], v[32:35]
	v_mfma_f32_16x16x32_bf16 v[20:23], v[176:179], v[212:215], v[20:23]
	v_mfma_f32_16x16x32_bf16 v[16:19], v[184:187], v[212:215], v[16:19]
	v_mfma_f32_16x16x32_bf16 v[4:7], v[176:179], v[220:223], v[4:7]
	v_mfma_f32_16x16x32_bf16 v[0:3], v[184:187], v[220:223], v[0:3]
	s_setprio 0
	s_barrier
	s_add_i32 s64, 0, 0x18000
	v_add_u32_e32 v136, s64, v162
	s_add_i32 s65, 0, 0x1c000
	ds_read_b128 v[146:149], v136
	ds_read_b128 v[154:157], v136 offset:1024
	ds_read_b128 v[158:161], v136 offset:2048
	ds_read_b128 v[168:171], v136 offset:3072
	v_add_u32_e32 v136, s65, v162
	ds_read_b128 v[172:175], v136
	ds_read_b128 v[176:179], v136 offset:1024
	ds_read_b128 v[180:183], v136 offset:2048
	ds_read_b128 v[184:187], v136 offset:3072
	s_add_u32 s42, s42, 0x80000
	s_addc_u32 s43, s43, 0
	s_mov_b32 m0, s47
	v_lshl_add_u64 v[228:229], s[42:43], 0, v[128:129]
	ds_read_b128 v[188:191], v166 offset:32768
	ds_read_b128 v[196:199], v166 offset:33792
	ds_read_b128 v[200:203], v166 offset:34816
	ds_read_b128 v[204:207], v166 offset:35840
	ds_read_b128 v[208:211], v166 offset:36864
	ds_read_b128 v[212:215], v166 offset:37888
	ds_read_b128 v[216:219], v166 offset:38912
	ds_read_b128 v[220:223], v166 offset:39936
	global_load_lds_dwordx4 v[228:229], off
	v_lshl_add_u64 v[228:229], s[42:43], 0, v[132:133]
	s_mov_b32 m0, s48
	s_nop 0
	global_load_lds_dwordx4 v[228:229], off
	s_waitcnt vmcnt(8)
	s_waitcnt lgkmcnt(0)
	s_barrier
	s_setprio 1
	s_waitcnt lgkmcnt(0)
	v_mfma_f32_16x16x32_bf16 v[124:127], v[146:149], v[188:191], v[124:127]
	v_mfma_f32_16x16x32_bf16 v[120:123], v[158:161], v[188:191], v[120:123]
	v_mfma_f32_16x16x32_bf16 v[108:111], v[146:149], v[200:203], v[108:111]
	v_mfma_f32_16x16x32_bf16 v[104:107], v[158:161], v[200:203], v[104:107]
	v_mfma_f32_16x16x32_bf16 v[92:95], v[146:149], v[208:211], v[92:95]
	v_mfma_f32_16x16x32_bf16 v[88:91], v[158:161], v[208:211], v[88:91]
	v_mfma_f32_16x16x32_bf16 v[76:79], v[146:149], v[216:219], v[76:79]
	v_mfma_f32_16x16x32_bf16 v[72:75], v[158:161], v[216:219], v[72:75]
	v_mfma_f32_16x16x32_bf16 v[124:127], v[154:157], v[196:199], v[124:127]
	v_mfma_f32_16x16x32_bf16 v[120:123], v[168:171], v[196:199], v[120:123]
	v_mfma_f32_16x16x32_bf16 v[108:111], v[154:157], v[204:207], v[108:111]
	v_mfma_f32_16x16x32_bf16 v[104:107], v[168:171], v[204:207], v[104:107]
	v_mfma_f32_16x16x32_bf16 v[92:95], v[154:157], v[212:215], v[92:95]
	v_mfma_f32_16x16x32_bf16 v[88:91], v[168:171], v[212:215], v[88:91]
	v_mfma_f32_16x16x32_bf16 v[76:79], v[154:157], v[220:223], v[76:79]
	v_mfma_f32_16x16x32_bf16 v[72:75], v[168:171], v[220:223], v[72:75]
	s_setprio 0
	s_setprio 1
	v_mfma_f32_16x16x32_bf16 v[116:119], v[172:175], v[188:191], v[116:119]
	v_mfma_f32_16x16x32_bf16 v[112:115], v[180:183], v[188:191], v[112:115]
	v_mfma_f32_16x16x32_bf16 v[100:103], v[172:175], v[200:203], v[100:103]
	v_mfma_f32_16x16x32_bf16 v[96:99], v[180:183], v[200:203], v[96:99]
	v_mfma_f32_16x16x32_bf16 v[84:87], v[172:175], v[208:211], v[84:87]
	v_mfma_f32_16x16x32_bf16 v[80:83], v[180:183], v[208:211], v[80:83]
	v_mfma_f32_16x16x32_bf16 v[68:71], v[172:175], v[216:219], v[68:71]
	v_mfma_f32_16x16x32_bf16 v[64:67], v[180:183], v[216:219], v[64:67]
	v_mfma_f32_16x16x32_bf16 v[116:119], v[176:179], v[196:199], v[116:119]
	v_mfma_f32_16x16x32_bf16 v[112:115], v[184:187], v[196:199], v[112:115]
	v_mfma_f32_16x16x32_bf16 v[100:103], v[176:179], v[204:207], v[100:103]
	v_mfma_f32_16x16x32_bf16 v[96:99], v[184:187], v[204:207], v[96:99]
	v_mfma_f32_16x16x32_bf16 v[84:87], v[176:179], v[212:215], v[84:87]
	v_mfma_f32_16x16x32_bf16 v[80:83], v[184:187], v[212:215], v[80:83]
	v_mfma_f32_16x16x32_bf16 v[68:71], v[176:179], v[220:223], v[68:71]
	v_mfma_f32_16x16x32_bf16 v[64:67], v[184:187], v[220:223], v[64:67]
	s_setprio 0
	s_barrier
; #define PG8_STAGE(bufoff, gbase, voff) do { _Pragma("unroll") for (int _i = 0; _i < 2; ++_i) \
;         __builtin_amdgcn_global_load_lds((const unsigned*)((const char*)(gbase) + (voff)[_i]), (PG8_LAS unsigned*)(lds + (bufoff) + ldsw + _i * 8192), 16, 0, 0); } while (0)
; #define PG8_LDA(dst, b, h) do { _Pragma("unroll") for (int m = 0; m < 4; ++m) _Pragma("unroll") for (int k = 0; k < 2; ++k) dst[m][k] = *(const PG8_LAS bf16x8*)(lds + PG8_SA(b, h) + aoff + m * 2048 + k * 1024); } while (0)
; #define PG8_MMA(ai, bj, At, Bt) do { __builtin_amdgcn_s_setprio(1); _Pragma("unroll") for (int m = 0; m < 4; ++m) _Pragma("unroll") for (int n = 0; n < 2; ++n) _Pragma("unroll") for (int k = 0; k < 2; ++k) \
;         acc[ai][bj][m][n] = __builtin_amdgcn_mfma_f32_16x16x32_bf16(Bt[n][k], At[m][k], acc[ai][bj][m][n], 0, 0, 0); __builtin_amdgcn_s_setprio(0); } while (0)
; #define PG8_WAIT_V(n) asm volatile("s_waitcnt vmcnt(" #n ")" ::: "memory")
; #define PG8_WAIT_L(n) asm volatile("s_waitcnt lgkmcnt(" #n ")" ::: "memory")
; #define PG8_BAR __builtin_amdgcn_s_barrier()
; #define PG8_SCHED __builtin_amdgcn_sched_barrier(0)
; template <class Epi, class Sched, bool ALIGN_EPI = false, bool SP2 = false>
; __device__ __forceinline__ void gemm_phase(PG8_LAS unsigned char* lds, const Gemm g, const Sched& S, const Epi& E, const int wave_) {
;     ...
;         for (int t = 0; t < nt; t += 2) {
;             const bool last = (t == nt - 2);
;     ...
;             PG8_LDA(At, 1, 1); PG8_STAGE(PG8_SB(1, 0), b3, voffB); PG8_STAGE(PG8_SB(1, 1), b3 + hstep, voffB); PG8_STAGE(PG8_SA(1, 0), a3, voffA);
;             PG8_WAIT_V(8); PG8_WAIT_L(0); PG8_BAR; PG8_MMA(1, 0, At, B0); PG8_MMA(1, 1, At, B1); PG8_BAR; PG8_SCHED;
	s_add_i32 s42, s64, s44
	v_lshl_add_u64 v[150:151], v[150:151], 0, s[18:19]
	s_mov_b32 m0, s42
	ds_read_b128 v[188:191], v166 offset:49152
	ds_read_b128 v[196:199], v166 offset:50176
	ds_read_b128 v[200:203], v166 offset:51200
	ds_read_b128 v[204:207], v166 offset:52224
	ds_read_b128 v[208:211], v166 offset:53248
	ds_read_b128 v[212:215], v166 offset:54272
	ds_read_b128 v[216:219], v166 offset:55296
	ds_read_b128 v[220:223], v166 offset:56320
	global_load_lds_dwordx4 v[150:151], off
	s_add_i32 m0, s42, 0x2000
	s_add_u32 s40, s40, 0x80080
	v_lshl_add_u64 v[150:151], v[192:193], 0, s[18:19]
	s_addc_u32 s41, s41, 0
	s_add_i32 s42, s65, s44
	global_load_lds_dwordx4 v[150:151], off
	v_lshl_add_u64 v[150:151], s[40:41], 0, v[130:131]
	s_mov_b32 m0, s42
	s_nop 0
	global_load_lds_dwordx4 v[150:151], off
	v_lshl_add_u64 v[150:151], s[40:41], 0, v[134:135]
	s_add_i32 m0, s42, 0x2000
	s_nop 0
	global_load_lds_dwordx4 v[150:151], off
	v_lshl_add_u64 v[150:151], v[224:225], 0, s[18:19]
	s_mov_b32 m0, s52
	s_nop 0
	global_load_lds_dwordx4 v[150:151], off
	v_lshl_add_u64 v[150:151], v[226:227], 0, s[18:19]
	s_mov_b32 m0, s53
	s_nop 0
	global_load_lds_dwordx4 v[150:151], off
	s_waitcnt vmcnt(8)
	s_waitcnt lgkmcnt(0)
	s_barrier
	s_setprio 1
	s_waitcnt lgkmcnt(0)
	v_mfma_f32_16x16x32_bf16 v[60:63], v[146:149], v[188:191], v[60:63]
	v_mfma_f32_16x16x32_bf16 v[56:59], v[158:161], v[188:191], v[56:59]
	v_mfma_f32_16x16x32_bf16 v[44:47], v[146:149], v[200:203], v[44:47]
	v_mfma_f32_16x16x32_bf16 v[40:43], v[158:161], v[200:203], v[40:43]
	v_mfma_f32_16x16x32_bf16 v[28:31], v[146:149], v[208:211], v[28:31]
	v_mfma_f32_16x16x32_bf16 v[24:27], v[158:161], v[208:211], v[24:27]
	v_mfma_f32_16x16x32_bf16 v[12:15], v[146:149], v[216:219], v[12:15]
	v_mfma_f32_16x16x32_bf16 v[8:11], v[158:161], v[216:219], v[8:11]
	v_mfma_f32_16x16x32_bf16 v[60:63], v[154:157], v[196:199], v[60:63]
	v_mfma_f32_16x16x32_bf16 v[56:59], v[168:171], v[196:199], v[56:59]
	v_mfma_f32_16x16x32_bf16 v[44:47], v[154:157], v[204:207], v[44:47]
	v_mfma_f32_16x16x32_bf16 v[40:43], v[168:171], v[204:207], v[40:43]
	v_mfma_f32_16x16x32_bf16 v[28:31], v[154:157], v[212:215], v[28:31]
	v_mfma_f32_16x16x32_bf16 v[24:27], v[168:171], v[212:215], v[24:27]
	v_mfma_f32_16x16x32_bf16 v[12:15], v[154:157], v[220:223], v[12:15]
	v_mfma_f32_16x16x32_bf16 v[8:11], v[168:171], v[220:223], v[8:11]
	s_setprio 0
	s_setprio 1
	v_mfma_f32_16x16x32_bf16 v[52:55], v[172:175], v[188:191], v[52:55]
	v_mfma_f32_16x16x32_bf16 v[48:51], v[180:183], v[188:191], v[48:51]
	v_mfma_f32_16x16x32_bf16 v[36:39], v[172:175], v[200:203], v[36:39]
	v_mfma_f32_16x16x32_bf16 v[32:35], v[180:183], v[200:203], v[32:35]
	v_mfma_f32_16x16x32_bf16 v[20:23], v[172:175], v[208:211], v[20:23]
	v_mfma_f32_16x16x32_bf16 v[16:19], v[180:183], v[208:211], v[16:19]
	v_mfma_f32_16x16x32_bf16 v[4:7], v[172:175], v[216:219], v[4:7]
	v_mfma_f32_16x16x32_bf16 v[0:3], v[180:183], v[216:219], v[0:3]
	v_mfma_f32_16x16x32_bf16 v[52:55], v[176:179], v[196:199], v[52:55]
	v_mfma_f32_16x16x32_bf16 v[48:51], v[184:187], v[196:199], v[48:51]
	v_mfma_f32_16x16x32_bf16 v[36:39], v[176:179], v[204:207], v[36:39]
	v_mfma_f32_16x16x32_bf16 v[32:35], v[184:187], v[204:207], v[32:35]
	v_mfma_f32_16x16x32_bf16 v[20:23], v[176:179], v[212:215], v[20:23]
	v_mfma_f32_16x16x32_bf16 v[16:19], v[184:187], v[212:215], v[16:19]
	v_mfma_f32_16x16x32_bf16 v[4:7], v[176:179], v[220:223], v[4:7]
	v_mfma_f32_16x16x32_bf16 v[0:3], v[184:187], v[220:223], v[0:3]
	s_setprio 0
	s_add_i32 s63, s63, 2
	s_add_u32 s36, s36, 0x100
	s_addc_u32 s37, s37, 0
	s_add_u32 s61, s61, 0x100
	s_addc_u32 s62, s62, 0
	s_cmp_gt_u32 s63, 29
	s_barrier
	s_cbranch_scc0 .LBB0_495
	s_and_b64 vcc, exec, s[16:17]
	s_cbranch_vccz .LBB0_498
	s_barrier

; #define PG8_STAGE(bufoff, gbase, voff) do { _Pragma("unroll") for (int _i = 0; _i < 2; ++_i) \
;         __builtin_amdgcn_global_load_lds((const unsigned*)((const char*)(gbase) + (voff)[_i]), (PG8_LAS unsigned*)(lds + (bufoff) + ldsw + _i * 8192), 16, 0, 0); } while (0)
; #define PG8_LDA(dst, b, h) do { _Pragma("unroll") for (int m = 0; m < 4; ++m) _Pragma("unroll") for (int k = 0; k < 2; ++k) dst[m][k] = *(const PG8_LAS bf16x8*)(lds + PG8_SA(b, h) + aoff + m * 2048 + k * 1024); } while (0)
; #define PG8_LDB(dst, b, h) do { _Pragma("unroll") for (int n = 0; n < 2; ++n) _Pragma("unroll") for (int k = 0; k < 2; ++k) dst[n][k] = *(const PG8_LAS bf16x8*)(lds + PG8_SB(b, h) + boff + n * 2048 + k * 1024); } while (0)
; #define PG8_MMA(ai, bj, At, Bt) do { __builtin_amdgcn_s_setprio(1); _Pragma("unroll") for (int m = 0; m < 4; ++m) _Pragma("unroll") for (int n = 0; n < 2; ++n) _Pragma("unroll") for (int k = 0; k < 2; ++k) \
;         acc[ai][bj][m][n] = __builtin_amdgcn_mfma_f32_16x16x32_bf16(Bt[n][k], At[m][k], acc[ai][bj][m][n], 0, 0, 0); __builtin_amdgcn_s_setprio(0); } while (0)
; #define PG8_WAIT_V(n) asm volatile("s_waitcnt vmcnt(" #n ")" ::: "memory")
; #define PG8_WAIT_L(n) asm volatile("s_waitcnt lgkmcnt(" #n ")" ::: "memory")
; #define PG8_BAR __builtin_amdgcn_s_barrier()
; #define PG8_SCHED __builtin_amdgcn_sched_barrier(0)
; template <class Epi, class Sched, bool ALIGN_EPI = false, bool SP2 = false>
; __device__ __forceinline__ void gemm_phase(PG8_LAS unsigned char* lds, const Gemm g, const Sched& S, const Epi& E, const int wave_) {
;     ...
;             const char* a1 = cA + (size_t)(t + 1) * kstep;
;             const char* a2 = last ? nA : cA + (size_t)(t + 2) * kstep; const char* b2 = last ? nB : cB + (size_t)(t + 2) * kstep;
;             const char* a3 = a2 + kstep; const char* b3 = b2 + kstep;
;     ...
;             PG8_LDB(B0, 0, 0); PG8_LDB(B1, 0, 1); PG8_SCHED; PG8_LDA(At, 0, 0); PG8_STAGE(PG8_SA(1, 1), a1 + hstep, voffA);
;             PG8_WAIT_V(8); PG8_WAIT_L(0); PG8_BAR; PG8_MMA(0, 0, At, B0); PG8_MMA(0, 1, At, B1); PG8_BAR; PG8_SCHED;
;             PG8_LDA(At, 0, 1); PG8_STAGE(PG8_SB(0, 0), b2, voffB); PG8_STAGE(PG8_SB(0, 1), b2 + hstep, voffB); PG8_STAGE(PG8_SA(0, 0), a2, voffA);
.LBB0_700:
	ds_read_b128 v[128:131], v187
	ds_read_b128 v[132:135], v187 offset:1024
	ds_read_b128 v[136:139], v187 offset:2048
	ds_read_b128 v[140:143], v187 offset:3072
	ds_read_b128 v[160:163], v188
	ds_read_b128 v[164:167], v188 offset:1024
	ds_read_b128 v[168:171], v188 offset:2048
	ds_read_b128 v[172:175], v188 offset:3072
	s_add_u32 s36, s34, 0xfff80080
	s_addc_u32 s37, s35, -1
	s_cmp_eq_u32 s58, 28
	s_cselect_b32 s41, s23, s37
	s_cselect_b32 s40, s29, s36
	s_cselect_b32 s37, s21, s57
	s_cselect_b32 s36, s31, s56
	v_lshl_add_u64 v[180:181], s[34:35], 0, v[152:153]
	s_add_i32 m0, s42, 0xc000
	ds_read_b128 v[176:179], v189
	ds_read_b128 v[196:199], v189 offset:1024
	ds_read_b128 v[200:203], v189 offset:2048
	ds_read_b128 v[204:207], v189 offset:3072
	ds_read_b128 v[208:211], v189 offset:4096
	ds_read_b128 v[212:215], v189 offset:5120
	ds_read_b128 v[216:219], v189 offset:6144
	ds_read_b128 v[220:223], v189 offset:7168
	global_load_lds_dwordx4 v[180:181], off
	v_lshl_add_u64 v[180:181], s[34:35], 0, v[154:155]
	s_add_i32 m0, s42, 0xe000
	s_nop 0
	global_load_lds_dwordx4 v[180:181], off
	s_waitcnt vmcnt(8)
	s_waitcnt lgkmcnt(0)
	s_barrier
	s_setprio 1
	s_waitcnt lgkmcnt(0)
	v_mfma_f32_16x16x32_bf16 v[40:43], v[128:131], v[176:179], v[40:43]
	v_mfma_f32_16x16x32_bf16 v[36:39], v[136:139], v[176:179], v[36:39]
	v_mfma_f32_16x16x32_bf16 v[68:71], v[128:131], v[200:203], v[68:71]
	v_mfma_f32_16x16x32_bf16 v[64:67], v[136:139], v[200:203], v[64:67]
	v_mfma_f32_16x16x32_bf16 v[100:103], v[128:131], v[208:211], v[100:103]
	v_mfma_f32_16x16x32_bf16 v[96:99], v[136:139], v[208:211], v[96:99]
	v_mfma_f32_16x16x32_bf16 v[124:127], v[128:131], v[216:219], v[124:127]
	v_mfma_f32_16x16x32_bf16 v[120:123], v[136:139], v[216:219], v[120:123]
	v_mfma_f32_16x16x32_bf16 v[40:43], v[132:135], v[196:199], v[40:43]
	v_mfma_f32_16x16x32_bf16 v[36:39], v[140:143], v[196:199], v[36:39]
	v_mfma_f32_16x16x32_bf16 v[68:71], v[132:135], v[204:207], v[68:71]
	v_mfma_f32_16x16x32_bf16 v[64:67], v[140:143], v[204:207], v[64:67]
	v_mfma_f32_16x16x32_bf16 v[100:103], v[132:135], v[212:215], v[100:103]
	v_mfma_f32_16x16x32_bf16 v[96:99], v[140:143], v[212:215], v[96:99]
	v_mfma_f32_16x16x32_bf16 v[124:127], v[132:135], v[220:223], v[124:127]
	v_mfma_f32_16x16x32_bf16 v[120:123], v[140:143], v[220:223], v[120:123]
	s_setprio 0
	s_setprio 1
	v_mfma_f32_16x16x32_bf16 v[44:47], v[160:163], v[176:179], v[44:47]
	v_mfma_f32_16x16x32_bf16 v[52:55], v[168:171], v[176:179], v[52:55]
	v_mfma_f32_16x16x32_bf16 v[72:75], v[160:163], v[200:203], v[72:75]
	v_mfma_f32_16x16x32_bf16 v[76:79], v[168:171], v[200:203], v[76:79]
	v_mfma_f32_16x16x32_bf16 v[104:107], v[160:163], v[208:211], v[104:107]
	v_mfma_f32_16x16x32_bf16 v[108:111], v[168:171], v[208:211], v[108:111]
	v_mfma_f32_16x16x32_bf16 v[116:119], v[160:163], v[216:219], v[116:119]
	v_mfma_f32_16x16x32_bf16 v[112:115], v[168:171], v[216:219], v[112:115]
	v_mfma_f32_16x16x32_bf16 v[44:47], v[164:167], v[196:199], v[44:47]
	v_mfma_f32_16x16x32_bf16 v[52:55], v[172:175], v[196:199], v[52:55]
	v_mfma_f32_16x16x32_bf16 v[72:75], v[164:167], v[204:207], v[72:75]
	v_mfma_f32_16x16x32_bf16 v[76:79], v[172:175], v[204:207], v[76:79]
	v_mfma_f32_16x16x32_bf16 v[104:107], v[164:167], v[212:215], v[104:107]
	v_mfma_f32_16x16x32_bf16 v[108:111], v[172:175], v[212:215], v[108:111]
	v_mfma_f32_16x16x32_bf16 v[116:119], v[164:167], v[220:223], v[116:119]
	v_mfma_f32_16x16x32_bf16 v[112:115], v[172:175], v[220:223], v[112:115]
	s_setprio 0
	s_barrier
	s_add_i32 s59, s54, s2
	v_lshl_add_u64 v[180:181], s[36:37], 0, v[146:147]
	s_mov_b32 m0, s59
	ds_read_b128 v[176:179], v189 offset:16384
	ds_read_b128 v[196:199], v189 offset:17408
	ds_read_b128 v[200:203], v189 offset:18432
	ds_read_b128 v[204:207], v189 offset:19456
	ds_read_b128 v[208:211], v189 offset:20480
	ds_read_b128 v[212:215], v189 offset:21504
	ds_read_b128 v[216:219], v189 offset:22528
	ds_read_b128 v[220:223], v189 offset:23552
	global_load_lds_dwordx4 v[180:181], off
	s_add_i32 m0, s59, 0x2000
	s_add_u32 s60, s36, 0x80000
	v_lshl_add_u64 v[192:193], s[36:37], 0, v[150:151]
	s_addc_u32 s61, s37, 0
	s_add_i32 s59, s55, s2
	global_load_lds_dwordx4 v[192:193], off
	v_lshl_add_u64 v[224:225], s[60:61], 0, v[146:147]
	s_mov_b32 m0, s59
	v_lshl_add_u64 v[226:227], s[40:41], 0, v[148:149]
	global_load_lds_dwordx4 v[224:225], off
	v_lshl_add_u64 v[224:225], s[60:61], 0, v[150:151]
	s_add_i32 m0, s59, 0x2000
	s_nop 0
	global_load_lds_dwordx4 v[224:225], off
	v_lshl_add_u64 v[224:225], s[40:41], 0, v[144:145]
	s_mov_b32 m0, s42
	s_nop 0
	global_load_lds_dwordx4 v[224:225], off
	s_mov_b32 m0, s43
	s_nop 0
	global_load_lds_dwordx4 v[226:227], off
	s_waitcnt vmcnt(8)
	s_waitcnt lgkmcnt(0)
	s_barrier
; #define PG8_STAGE(bufoff, gbase, voff) do { _Pragma("unroll") for (int _i = 0; _i < 2; ++_i) \
;         __builtin_amdgcn_global_load_lds((const unsigned*)((const char*)(gbase) + (voff)[_i]), (PG8_LAS unsigned*)(lds + (bufoff) + ldsw + _i * 8192), 16, 0, 0); } while (0)
; #define PG8_LDA(dst, b, h) do { _Pragma("unroll") for (int m = 0; m < 4; ++m) _Pragma("unroll") for (int k = 0; k < 2; ++k) dst[m][k] = *(const PG8_LAS bf16x8*)(lds + PG8_SA(b, h) + aoff + m * 2048 + k * 1024); } while (0)
; #define PG8_LDB(dst, b, h) do { _Pragma("unroll") for (int n = 0; n < 2; ++n) _Pragma("unroll") for (int k = 0; k < 2; ++k) dst[n][k] = *(const PG8_LAS bf16x8*)(lds + PG8_SB(b, h) + boff + n * 2048 + k * 1024); } while (0)
; #define PG8_MMA(ai, bj, At, Bt) do { __builtin_amdgcn_s_setprio(1); _Pragma("unroll") for (int m = 0; m < 4; ++m) _Pragma("unroll") for (int n = 0; n < 2; ++n) _Pragma("unroll") for (int k = 0; k < 2; ++k) \
;         acc[ai][bj][m][n] = __builtin_amdgcn_mfma_f32_16x16x32_bf16(Bt[n][k], At[m][k], acc[ai][bj][m][n], 0, 0, 0); __builtin_amdgcn_s_setprio(0); } while (0)
; #define PG8_WAIT_V(n) asm volatile("s_waitcnt vmcnt(" #n ")" ::: "memory")
; #define PG8_WAIT_L(n) asm volatile("s_waitcnt lgkmcnt(" #n ")" ::: "memory")
; #define PG8_BAR __builtin_amdgcn_s_barrier()
; #define PG8_SCHED __builtin_amdgcn_sched_barrier(0)
; template <class Epi, class Sched, bool ALIGN_EPI = false, bool SP2 = false>
; __device__ __forceinline__ void gemm_phase(PG8_LAS unsigned char* lds, const Gemm g, const Sched& S, const Epi& E, const int wave_) {
;     ...
;             PG8_WAIT_V(8); PG8_WAIT_L(0); PG8_BAR; PG8_MMA(1, 0, At, B0); PG8_MMA(1, 1, At, B1); PG8_BAR; PG8_SCHED;
;             PG8_LDB(B0, 1, 0); PG8_LDB(B1, 1, 1); PG8_SCHED; PG8_LDA(At, 1, 0); PG8_STAGE(PG8_SA(0, 1), a2 + hstep, voffA);
;             PG8_WAIT_V(8); PG8_WAIT_L(0); PG8_BAR; PG8_MMA(0, 0, At, B0); PG8_MMA(0, 1, At, B1); PG8_BAR; PG8_SCHED;
	s_setprio 1
	s_waitcnt lgkmcnt(0)
	v_mfma_f32_16x16x32_bf16 v[92:95], v[128:131], v[176:179], v[92:95]
	v_mfma_f32_16x16x32_bf16 v[88:91], v[136:139], v[176:179], v[88:91]
	v_mfma_f32_16x16x32_bf16 v[60:63], v[128:131], v[200:203], v[60:63]
	v_mfma_f32_16x16x32_bf16 v[56:59], v[136:139], v[200:203], v[56:59]
	v_mfma_f32_16x16x32_bf16 v[28:31], v[128:131], v[208:211], v[28:31]
	v_mfma_f32_16x16x32_bf16 v[24:27], v[136:139], v[208:211], v[24:27]
	v_mfma_f32_16x16x32_bf16 v[12:15], v[128:131], v[216:219], v[12:15]
	v_mfma_f32_16x16x32_bf16 v[8:11], v[136:139], v[216:219], v[8:11]
	v_mfma_f32_16x16x32_bf16 v[92:95], v[132:135], v[196:199], v[92:95]
	v_mfma_f32_16x16x32_bf16 v[88:91], v[140:143], v[196:199], v[88:91]
	v_mfma_f32_16x16x32_bf16 v[60:63], v[132:135], v[204:207], v[60:63]
	v_mfma_f32_16x16x32_bf16 v[56:59], v[140:143], v[204:207], v[56:59]
	v_mfma_f32_16x16x32_bf16 v[28:31], v[132:135], v[212:215], v[28:31]
	v_mfma_f32_16x16x32_bf16 v[24:27], v[140:143], v[212:215], v[24:27]
	v_mfma_f32_16x16x32_bf16 v[12:15], v[132:135], v[220:223], v[12:15]
	v_mfma_f32_16x16x32_bf16 v[8:11], v[140:143], v[220:223], v[8:11]
	s_setprio 0
	s_setprio 1
	v_mfma_f32_16x16x32_bf16 v[84:87], v[160:163], v[176:179], v[84:87]
	v_mfma_f32_16x16x32_bf16 v[80:83], v[168:171], v[176:179], v[80:83]
	v_mfma_f32_16x16x32_bf16 v[48:51], v[160:163], v[200:203], v[48:51]
	v_mfma_f32_16x16x32_bf16 v[32:35], v[168:171], v[200:203], v[32:35]
	v_mfma_f32_16x16x32_bf16 v[20:23], v[160:163], v[208:211], v[20:23]
	v_mfma_f32_16x16x32_bf16 v[16:19], v[168:171], v[208:211], v[16:19]
	v_mfma_f32_16x16x32_bf16 v[4:7], v[160:163], v[216:219], v[4:7]
	v_mfma_f32_16x16x32_bf16 v[0:3], v[168:171], v[216:219], v[0:3]
	v_mfma_f32_16x16x32_bf16 v[84:87], v[164:167], v[196:199], v[84:87]
	v_mfma_f32_16x16x32_bf16 v[80:83], v[172:175], v[196:199], v[80:83]
	v_mfma_f32_16x16x32_bf16 v[48:51], v[164:167], v[204:207], v[48:51]
	v_mfma_f32_16x16x32_bf16 v[32:35], v[172:175], v[204:207], v[32:35]
	v_mfma_f32_16x16x32_bf16 v[20:23], v[164:167], v[212:215], v[20:23]
	v_mfma_f32_16x16x32_bf16 v[16:19], v[172:175], v[212:215], v[16:19]
	v_mfma_f32_16x16x32_bf16 v[4:7], v[164:167], v[220:223], v[4:7]
	v_mfma_f32_16x16x32_bf16 v[0:3], v[172:175], v[220:223], v[0:3]
	s_setprio 0
	s_barrier
	s_add_i32 s59, 0, 0x18000
	s_add_i32 s60, 0, 0x1c000
	v_add_u32_e32 v140, s59, v183
	v_add_u32_e32 v172, s60, v183
	ds_read_b128 v[128:131], v140
	ds_read_b128 v[132:135], v140 offset:1024
	ds_read_b128 v[136:139], v140 offset:2048
	ds_read_b128 v[140:143], v140 offset:3072
	ds_read_b128 v[160:163], v172
	ds_read_b128 v[164:167], v172 offset:1024
	ds_read_b128 v[168:171], v172 offset:2048
	ds_read_b128 v[172:175], v172 offset:3072
	s_add_u32 s40, s40, 0x80000
	s_addc_u32 s41, s41, 0
	s_mov_b32 m0, s44
	v_lshl_add_u64 v[228:229], s[40:41], 0, v[144:145]
	ds_read_b128 v[176:179], v189 offset:32768
	ds_read_b128 v[196:199], v189 offset:33792
	ds_read_b128 v[200:203], v189 offset:34816
	ds_read_b128 v[204:207], v189 offset:35840
	ds_read_b128 v[208:211], v189 offset:36864
	ds_read_b128 v[212:215], v189 offset:37888
	ds_read_b128 v[216:219], v189 offset:38912
	ds_read_b128 v[220:223], v189 offset:39936
	global_load_lds_dwordx4 v[228:229], off
	v_lshl_add_u64 v[228:229], s[40:41], 0, v[148:149]
	s_mov_b32 m0, s45
	s_nop 0
	global_load_lds_dwordx4 v[228:229], off
	s_waitcnt vmcnt(8)
	s_waitcnt lgkmcnt(0)
	s_barrier
	s_setprio 1
	s_waitcnt lgkmcnt(0)
	v_mfma_f32_16x16x32_bf16 v[40:43], v[128:131], v[176:179], v[40:43]
	v_mfma_f32_16x16x32_bf16 v[36:39], v[136:139], v[176:179], v[36:39]
	v_mfma_f32_16x16x32_bf16 v[68:71], v[128:131], v[200:203], v[68:71]
	v_mfma_f32_16x16x32_bf16 v[64:67], v[136:139], v[200:203], v[64:67]
	v_mfma_f32_16x16x32_bf16 v[100:103], v[128:131], v[208:211], v[100:103]
	v_mfma_f32_16x16x32_bf16 v[96:99], v[136:139], v[208:211], v[96:99]
	v_mfma_f32_16x16x32_bf16 v[124:127], v[128:131], v[216:219], v[124:127]
	v_mfma_f32_16x16x32_bf16 v[120:123], v[136:139], v[216:219], v[120:123]
	v_mfma_f32_16x16x32_bf16 v[40:43], v[132:135], v[196:199], v[40:43]
	v_mfma_f32_16x16x32_bf16 v[36:39], v[140:143], v[196:199], v[36:39]
	v_mfma_f32_16x16x32_bf16 v[68:71], v[132:135], v[204:207], v[68:71]
	v_mfma_f32_16x16x32_bf16 v[64:67], v[140:143], v[204:207], v[64:67]
	v_mfma_f32_16x16x32_bf16 v[100:103], v[132:135], v[212:215], v[100:103]
	v_mfma_f32_16x16x32_bf16 v[96:99], v[140:143], v[212:215], v[96:99]
	v_mfma_f32_16x16x32_bf16 v[124:127], v[132:135], v[220:223], v[124:127]
	v_mfma_f32_16x16x32_bf16 v[120:123], v[140:143], v[220:223], v[120:123]
	s_setprio 0
	s_setprio 1
	v_mfma_f32_16x16x32_bf16 v[44:47], v[160:163], v[176:179], v[44:47]
	v_mfma_f32_16x16x32_bf16 v[52:55], v[168:171], v[176:179], v[52:55]
	v_mfma_f32_16x16x32_bf16 v[72:75], v[160:163], v[200:203], v[72:75]
	v_mfma_f32_16x16x32_bf16 v[76:79], v[168:171], v[200:203], v[76:79]
	v_mfma_f32_16x16x32_bf16 v[104:107], v[160:163], v[208:211], v[104:107]
	v_mfma_f32_16x16x32_bf16 v[108:111], v[168:171], v[208:211], v[108:111]
	v_mfma_f32_16x16x32_bf16 v[116:119], v[160:163], v[216:219], v[116:119]
	v_mfma_f32_16x16x32_bf16 v[112:115], v[168:171], v[216:219], v[112:115]
	v_mfma_f32_16x16x32_bf16 v[44:47], v[164:167], v[196:199], v[44:47]
	v_mfma_f32_16x16x32_bf16 v[52:55], v[172:175], v[196:199], v[52:55]
	v_mfma_f32_16x16x32_bf16 v[72:75], v[164:167], v[204:207], v[72:75]
	v_mfma_f32_16x16x32_bf16 v[76:79], v[172:175], v[204:207], v[76:79]
	v_mfma_f32_16x16x32_bf16 v[104:107], v[164:167], v[212:215], v[104:107]
	v_mfma_f32_16x16x32_bf16 v[108:111], v[172:175], v[212:215], v[108:111]
	v_mfma_f32_16x16x32_bf16 v[116:119], v[164:167], v[220:223], v[116:119]
	v_mfma_f32_16x16x32_bf16 v[112:115], v[172:175], v[220:223], v[112:115]
	s_setprio 0
	s_barrier
; #define PG8_STAGE(bufoff, gbase, voff) do { _Pragma("unroll") for (int _i = 0; _i < 2; ++_i) \
;         __builtin_amdgcn_global_load_lds((const unsigned*)((const char*)(gbase) + (voff)[_i]), (PG8_LAS unsigned*)(lds + (bufoff) + ldsw + _i * 8192), 16, 0, 0); } while (0)
; #define PG8_LDA(dst, b, h) do { _Pragma("unroll") for (int m = 0; m < 4; ++m) _Pragma("unroll") for (int k = 0; k < 2; ++k) dst[m][k] = *(const PG8_LAS bf16x8*)(lds + PG8_SA(b, h) + aoff + m * 2048 + k * 1024); } while (0)
; #define PG8_MMA(ai, bj, At, Bt) do { __builtin_amdgcn_s_setprio(1); _Pragma("unroll") for (int m = 0; m < 4; ++m) _Pragma("unroll") for (int n = 0; n < 2; ++n) _Pragma("unroll") for (int k = 0; k < 2; ++k) \
;         acc[ai][bj][m][n] = __builtin_amdgcn_mfma_f32_16x16x32_bf16(Bt[n][k], At[m][k], acc[ai][bj][m][n], 0, 0, 0); __builtin_amdgcn_s_setprio(0); } while (0)
; #define PG8_WAIT_V(n) asm volatile("s_waitcnt vmcnt(" #n ")" ::: "memory")
; #define PG8_WAIT_L(n) asm volatile("s_waitcnt lgkmcnt(" #n ")" ::: "memory")
; #define PG8_BAR __builtin_amdgcn_s_barrier()
; #define PG8_SCHED __builtin_amdgcn_sched_barrier(0)
; template <class Epi, class Sched, bool ALIGN_EPI = false, bool SP2 = false>
; __device__ __forceinline__ void gemm_phase(PG8_LAS unsigned char* lds, const Gemm g, const Sched& S, const Epi& E, const int wave_) {
;     ...
;         for (int t = 0; t < nt; t += 2) {
;             const bool last = (t == nt - 2);
;     ...
;             PG8_LDA(At, 1, 1); PG8_STAGE(PG8_SB(1, 0), b3, voffB); PG8_STAGE(PG8_SB(1, 1), b3 + hstep, voffB); PG8_STAGE(PG8_SA(1, 0), a3, voffA);
;             PG8_WAIT_V(8); PG8_WAIT_L(0); PG8_BAR; PG8_MMA(1, 0, At, B0); PG8_MMA(1, 1, At, B1); PG8_BAR; PG8_SCHED;
	s_add_i32 s40, s59, s2
	v_lshl_add_u64 v[180:181], v[180:181], 0, s[18:19]
	s_mov_b32 m0, s40
	ds_read_b128 v[176:179], v189 offset:49152
	ds_read_b128 v[196:199], v189 offset:50176
	ds_read_b128 v[200:203], v189 offset:51200
	ds_read_b128 v[204:207], v189 offset:52224
	ds_read_b128 v[208:211], v189 offset:53248
	ds_read_b128 v[212:215], v189 offset:54272
	ds_read_b128 v[216:219], v189 offset:55296
	ds_read_b128 v[220:223], v189 offset:56320
	global_load_lds_dwordx4 v[180:181], off
	s_add_i32 m0, s40, 0x2000
	s_add_u32 s36, s36, 0x80080
	v_lshl_add_u64 v[180:181], v[192:193], 0, s[18:19]
	s_addc_u32 s37, s37, 0
	s_add_i32 s40, s60, s2
	global_load_lds_dwordx4 v[180:181], off
	v_lshl_add_u64 v[180:181], s[36:37], 0, v[146:147]
	s_mov_b32 m0, s40
	s_nop 0
	global_load_lds_dwordx4 v[180:181], off
	v_lshl_add_u64 v[180:181], s[36:37], 0, v[150:151]
	s_add_i32 m0, s40, 0x2000
	s_nop 0
	global_load_lds_dwordx4 v[180:181], off
	v_lshl_add_u64 v[180:181], v[224:225], 0, s[18:19]
	s_mov_b32 m0, s51
	s_nop 0
	global_load_lds_dwordx4 v[180:181], off
	v_lshl_add_u64 v[180:181], v[226:227], 0, s[18:19]
	s_mov_b32 m0, s52
	s_nop 0
	global_load_lds_dwordx4 v[180:181], off
	s_waitcnt vmcnt(8)
	s_waitcnt lgkmcnt(0)
	s_barrier
	s_setprio 1
	s_waitcnt lgkmcnt(0)
	v_mfma_f32_16x16x32_bf16 v[92:95], v[128:131], v[176:179], v[92:95]
	v_mfma_f32_16x16x32_bf16 v[88:91], v[136:139], v[176:179], v[88:91]
	v_mfma_f32_16x16x32_bf16 v[60:63], v[128:131], v[200:203], v[60:63]
	v_mfma_f32_16x16x32_bf16 v[56:59], v[136:139], v[200:203], v[56:59]
	v_mfma_f32_16x16x32_bf16 v[28:31], v[128:131], v[208:211], v[28:31]
	v_mfma_f32_16x16x32_bf16 v[24:27], v[136:139], v[208:211], v[24:27]
	v_mfma_f32_16x16x32_bf16 v[12:15], v[128:131], v[216:219], v[12:15]
	v_mfma_f32_16x16x32_bf16 v[8:11], v[136:139], v[216:219], v[8:11]
	v_mfma_f32_16x16x32_bf16 v[92:95], v[132:135], v[196:199], v[92:95]
	v_mfma_f32_16x16x32_bf16 v[88:91], v[140:143], v[196:199], v[88:91]
	v_mfma_f32_16x16x32_bf16 v[60:63], v[132:135], v[204:207], v[60:63]
	v_mfma_f32_16x16x32_bf16 v[56:59], v[140:143], v[204:207], v[56:59]
	v_mfma_f32_16x16x32_bf16 v[28:31], v[132:135], v[212:215], v[28:31]
	v_mfma_f32_16x16x32_bf16 v[24:27], v[140:143], v[212:215], v[24:27]
	v_mfma_f32_16x16x32_bf16 v[12:15], v[132:135], v[220:223], v[12:15]
	v_mfma_f32_16x16x32_bf16 v[8:11], v[140:143], v[220:223], v[8:11]
	s_setprio 0
	s_setprio 1
	v_mfma_f32_16x16x32_bf16 v[84:87], v[160:163], v[176:179], v[84:87]
	v_mfma_f32_16x16x32_bf16 v[80:83], v[168:171], v[176:179], v[80:83]
	v_mfma_f32_16x16x32_bf16 v[48:51], v[160:163], v[200:203], v[48:51]
	v_mfma_f32_16x16x32_bf16 v[32:35], v[168:171], v[200:203], v[32:35]
	v_mfma_f32_16x16x32_bf16 v[20:23], v[160:163], v[208:211], v[20:23]
	v_mfma_f32_16x16x32_bf16 v[16:19], v[168:171], v[208:211], v[16:19]
	v_mfma_f32_16x16x32_bf16 v[4:7], v[160:163], v[216:219], v[4:7]
	v_mfma_f32_16x16x32_bf16 v[0:3], v[168:171], v[216:219], v[0:3]
	v_mfma_f32_16x16x32_bf16 v[84:87], v[164:167], v[196:199], v[84:87]
	v_mfma_f32_16x16x32_bf16 v[80:83], v[172:175], v[196:199], v[80:83]
	v_mfma_f32_16x16x32_bf16 v[48:51], v[164:167], v[204:207], v[48:51]
	v_mfma_f32_16x16x32_bf16 v[32:35], v[172:175], v[204:207], v[32:35]
	v_mfma_f32_16x16x32_bf16 v[20:23], v[164:167], v[212:215], v[20:23]
	v_mfma_f32_16x16x32_bf16 v[16:19], v[172:175], v[212:215], v[16:19]
	v_mfma_f32_16x16x32_bf16 v[4:7], v[164:167], v[220:223], v[4:7]
	v_mfma_f32_16x16x32_bf16 v[0:3], v[172:175], v[220:223], v[0:3]
	s_setprio 0
	s_add_i32 s58, s58, 2
	s_add_u32 s34, s34, 0x100
	s_addc_u32 s35, s35, 0
	s_add_u32 s56, s56, 0x100
	s_addc_u32 s57, s57, 0
	s_cmp_gt_u32 s58, 29
	s_barrier
	s_cbranch_scc0 .LBB0_700
	s_and_b64 vcc, exec, s[14:15]
	s_cbranch_vccz .LBB0_703
	s_barrier
